# S5 chunk loop: 4-deep register ring for the U rows (unrolled x4, loads four chunks ahead with counted vmcnt instead of hipcc's rotate-and-wait), on top of the setup rewrite
# baseline (speedup 1.0000x reference)
.LBB0_840:
	s_or_b64 exec, exec, s[0:1]
	v_max_f32_e32 v2, v107, v107
	v_min_f32_e32 v2, 0xb8d1b717, v2
	v_mul_f32_e32 v2, v105, v2
	v_mul_f32_e32 v105, 0x3fb8aa3b, v2
	v_fma_f32 v107, v2, s27, -v105
	v_rndne_f32_e32 v128, v105
	v_fmac_f32_e32 v107, 0x32a5705f, v2
	v_sub_f32_e32 v105, v105, v128
	v_add_f32_e32 v105, v105, v107
	v_exp_f32_e32 v105, v105
	v_cvt_i32_f32_e32 v107, v128
	v_cmp_ngt_f32_e32 vcc, s29, v2
	s_waitcnt vmcnt(0)
	v_cvt_pk_bf16_f32 v60, v60, -v64
	v_xor_b32_e32 v125, v125, v124
	v_ldexp_f32 v105, v105, v107
	v_cndmask_b32_e32 v105, 0, v105, vcc
	v_cmp_nlt_f32_e32 vcc, s10, v2
	s_mul_i32 s0, s53, 0x1800000
	v_cmp_class_f32_e64 s[46:47], v124, s28
	v_cndmask_b32_e32 v2, v223, v105, vcc
	v_mul_f32_e32 v105, v126, v126
	v_fmamk_f32 v107, v105, 0xb94c1982, v219
	v_fmaak_f32 v107, v105, v107, 0xbe2aaa9d
	v_mul_f32_e32 v107, v105, v107
	v_fmac_f32_e32 v126, v126, v107
	v_fmamk_f32 v107, v105, 0x37d75334, v220
	v_fmaak_f32 v107, v105, v107, 0x3d2aabf7
	v_fmaak_f32 v107, v105, v107, 0xbf000004
	v_fma_f32 v105, v105, v107, 1.0
	v_lshlrev_b32_e32 v107, 30, v127
	v_and_b32_e32 v127, 1, v127
	v_cmp_eq_u32_e32 vcc, 0, v127
	v_xor_b32_e32 v64, 0x80000000, v126
	v_and_b32_e32 v128, 0x80000000, v107
	v_cndmask_b32_e32 v127, v105, v126, vcc
	v_cndmask_b32_e32 v64, v64, v105, vcc
	v_xor_b32_e32 v125, v125, v127
	v_bitop3_b32 v64, v64, v107, s33 bitop3:0x78
	s_add_u32 s12, s20, s0
	v_xor_b32_e32 v125, v125, v128
	v_cndmask_b32_e64 v64, v251, v64, s[46:47]
	s_addc_u32 s13, s21, 0
	v_cndmask_b32_e64 v124, v251, v125, s[46:47]
	v_cvt_pk_bf16_f32 v58, v58, -v74
	v_cvt_pk_bf16_f32 v61, v61, -v65
	v_mul_f32_e32 v74, v2, v64
	v_lshlrev_b64 v[64:65], 1, v[122:123]
	v_cvt_pk_bf16_f32 v52, v52, -v76
	v_cvt_pk_bf16_f32 v53, v53, -v77
	v_cvt_pk_bf16_f32 v56, v56, -v72
	v_mul_f32_e32 v72, v2, v124
	s_cmp_eq_u32 s53, 0
	v_lshl_add_u64 v[76:77], v[90:91], 0, v[64:65]
	v_lshl_add_u64 v[64:65], s[12:13], 0, v[64:65]
	s_mov_b32 s3, 0
	v_cvt_pk_bf16_f32 v48, v48, -v80
	v_cvt_pk_bf16_f32 v49, v49, -v81
	v_cvt_pk_bf16_f32 v50, v50, -v82
	v_cvt_pk_bf16_f32 v51, v51, -v83
	v_cvt_pk_bf16_f32 v54, v54, -v78
	v_cvt_pk_bf16_f32 v55, v55, -v79
	v_cvt_pk_bf16_f32 v57, v57, -v73
	v_cvt_pk_bf16_f32 v59, v59, -v75
	v_cvt_pk_bf16_f32 v62, v62, -v66
	v_cvt_pk_bf16_f32 v63, v63, -v67
	s_cselect_b64 s[0:1], -1, 0
	s_add_i32 s4, s2, -5
	v_lshl_add_u64 v[78:79], v[86:87], 1, v[64:65]
	v_mov_b32_e32 v75, v74
	v_mov_b32_e32 v73, v72
	s_add_i32 s18, s2, -5
	s_mov_b32 s98, 0x10000
	s_and_b64 s[14:15], s[0:1], exec
	s_cselect_b32 s18, 4, s18
	s_cselect_b32 s99, 0, -1
	s_cselect_b32 s98, s98, 0xffff0000
	v_lshl_add_u32 v64, s18, 4, v103
	v_ashrrev_i32_e32 v65, 31, v64
	v_lshlrev_b64 v[64:65], 12, v[64:65]
	v_lshl_add_u64 v[64:65], v[76:77], 0, v[64:65]
.Ls5c_main:
	s_waitcnt vmcnt(7)
	v_mfma_f32_16x16x32_bf16 v[132:135], v[4:7], v[68:71], 0
	v_mfma_f32_16x16x32_bf16 v[136:139], v[8:11], v[68:71], 0
	v_mfma_f32_16x16x32_bf16 v[140:143], v[12:15], v[68:71], 0
	v_mfma_f32_16x16x32_bf16 v[144:147], v[16:19], v[68:71], 0
	v_mfma_f32_16x16x32_bf16 v[148:151], v[20:23], v[68:71], 0
	v_mfma_f32_16x16x32_bf16 v[152:155], v[24:27], v[68:71], 0
	v_mfma_f32_16x16x32_bf16 v[156:159], v[28:31], v[68:71], 0
	v_mfma_f32_16x16x32_bf16 v[160:163], v[32:35], v[68:71], 0
	s_and_saveexec_b64 s[12:13], s[40:41]
	global_load_dwordx4 v[68:71], v[64:65], off
	s_mov_b64 exec, s[12:13]
	v_lshl_add_u64 v[64:65], v[64:65], 0, s[98:99]
	v_add_u32_e32 v196, v89, v93
	ds_write_b128 v196, v[132:135]
	ds_write_b128 v196, v[136:139] offset:64
	ds_write_b128 v196, v[140:143] offset:128
	ds_write_b128 v196, v[144:147] offset:192
	ds_write_b128 v196, v[148:151] offset:256
	ds_write_b128 v196, v[152:155] offset:320
	ds_write_b128 v196, v[156:159] offset:384
	ds_write_b128 v196, v[160:163] offset:448
	s_waitcnt lgkmcnt(0)
	s_and_b64 s[14:15], s[0:1], exec
	s_cbranch_scc0 .Ls5cm0_bwd
	ds_read_b64 v[164:165], v95
	ds_read_b64 v[166:167], v95 offset:528
	ds_read_b64 v[168:169], v95 offset:1056
	ds_read_b64 v[170:171], v95 offset:1584
	ds_read_b64 v[172:173], v95 offset:2112
	ds_read_b64 v[174:175], v95 offset:2640
	ds_read_b64 v[176:177], v95 offset:3168
	ds_read_b64 v[178:179], v95 offset:3696
	s_waitcnt lgkmcnt(7)
	v_fma_f32 v164, -v72, v121, v164
	v_fma_f32 v165, v72, v120, v165
	v_fma_f32 v164, v74, v120, v164
	v_fma_f32 v165, v74, v121, v165
	v_cvt_pk_bf16_f32 v197, v164, v165
	ds_write_b32 v97, v197 offset:8448
	ds_read_b64 v[180:181], v95 offset:4224
	s_waitcnt lgkmcnt(8)
	v_fma_f32 v166, -v72, v165, v166
	v_fma_f32 v167, v72, v164, v167
	v_fma_f32 v166, v74, v164, v166
	v_fma_f32 v167, v74, v165, v167
	v_cvt_pk_bf16_f32 v198, v166, v167
	ds_write_b32 v97, v198 offset:8720
	ds_read_b64 v[182:183], v95 offset:4752
	s_waitcnt lgkmcnt(9)
	v_fma_f32 v168, -v72, v167, v168
	v_fma_f32 v169, v72, v166, v169
	v_fma_f32 v168, v74, v166, v168
	v_fma_f32 v169, v74, v167, v169
	v_cvt_pk_bf16_f32 v197, v168, v169
	ds_write_b32 v97, v197 offset:8992
	ds_read_b64 v[184:185], v95 offset:5280
	s_waitcnt lgkmcnt(10)
	v_fma_f32 v170, -v72, v169, v170
	v_fma_f32 v171, v72, v168, v171
	v_fma_f32 v170, v74, v168, v170
	v_fma_f32 v171, v74, v169, v171
	v_cvt_pk_bf16_f32 v198, v170, v171
	ds_write_b32 v97, v198 offset:9264
	ds_read_b64 v[186:187], v95 offset:5808
	s_waitcnt lgkmcnt(11)
	v_fma_f32 v172, -v72, v171, v172
	v_fma_f32 v173, v72, v170, v173
	v_fma_f32 v172, v74, v170, v172
	v_fma_f32 v173, v74, v171, v173
	v_cvt_pk_bf16_f32 v197, v172, v173
	ds_write_b32 v97, v197 offset:9536
	ds_read_b64 v[188:189], v95 offset:6336
	s_waitcnt lgkmcnt(12)
	v_fma_f32 v174, -v72, v173, v174
	v_fma_f32 v175, v72, v172, v175
	v_fma_f32 v174, v74, v172, v174
	v_fma_f32 v175, v74, v173, v175
	v_cvt_pk_bf16_f32 v198, v174, v175
	ds_write_b32 v97, v198 offset:9808
	ds_read_b64 v[190:191], v95 offset:6864
	s_waitcnt lgkmcnt(13)
	v_fma_f32 v176, -v72, v175, v176
	v_fma_f32 v177, v72, v174, v177
	v_fma_f32 v176, v74, v174, v176
	v_fma_f32 v177, v74, v175, v177
	v_cvt_pk_bf16_f32 v197, v176, v177
	ds_write_b32 v97, v197 offset:10080
	ds_read_b64 v[192:193], v95 offset:7392
	s_waitcnt lgkmcnt(14)
	v_fma_f32 v178, -v72, v177, v178
	v_fma_f32 v179, v72, v176, v179
	v_fma_f32 v178, v74, v176, v178
	v_fma_f32 v179, v74, v177, v179
	v_cvt_pk_bf16_f32 v198, v178, v179
	ds_write_b32 v97, v198 offset:10352
	ds_read_b64 v[194:195], v95 offset:7920
	s_waitcnt lgkmcnt(14)
	v_fma_f32 v180, -v72, v179, v180
	v_fma_f32 v181, v72, v178, v181
	v_fma_f32 v180, v74, v178, v180
	v_fma_f32 v181, v74, v179, v181
	v_cvt_pk_bf16_f32 v197, v180, v181
	ds_write_b32 v97, v197 offset:10624
	s_waitcnt lgkmcnt(13)
	v_fma_f32 v182, -v72, v181, v182
	v_fma_f32 v183, v72, v180, v183
	v_fma_f32 v182, v74, v180, v182
	v_fma_f32 v183, v74, v181, v183
	v_cvt_pk_bf16_f32 v198, v182, v183
	ds_write_b32 v97, v198 offset:10896
	s_waitcnt lgkmcnt(12)
	v_fma_f32 v184, -v72, v183, v184
	v_fma_f32 v185, v72, v182, v185
	v_fma_f32 v184, v74, v182, v184
	v_fma_f32 v185, v74, v183, v185
	v_cvt_pk_bf16_f32 v197, v184, v185
	ds_write_b32 v97, v197 offset:11168
	s_waitcnt lgkmcnt(11)
	v_fma_f32 v186, -v72, v185, v186
	v_fma_f32 v187, v72, v184, v187
	v_fma_f32 v186, v74, v184, v186
	v_fma_f32 v187, v74, v185, v187
	v_cvt_pk_bf16_f32 v198, v186, v187
	ds_write_b32 v97, v198 offset:11440
	s_waitcnt lgkmcnt(10)
	v_fma_f32 v188, -v72, v187, v188
	v_fma_f32 v189, v72, v186, v189
	v_fma_f32 v188, v74, v186, v188
	v_fma_f32 v189, v74, v187, v189
	v_cvt_pk_bf16_f32 v197, v188, v189
	ds_write_b32 v97, v197 offset:11712
	s_waitcnt lgkmcnt(9)
	v_fma_f32 v190, -v72, v189, v190
	v_fma_f32 v191, v72, v188, v191
	v_fma_f32 v190, v74, v188, v190
	v_fma_f32 v191, v74, v189, v191
	v_cvt_pk_bf16_f32 v198, v190, v191
	ds_write_b32 v97, v198 offset:11984
	s_waitcnt lgkmcnt(8)
	v_fma_f32 v192, -v72, v191, v192
	v_fma_f32 v193, v72, v190, v193
	v_fma_f32 v192, v74, v190, v192
	v_fma_f32 v193, v74, v191, v193
	v_cvt_pk_bf16_f32 v197, v192, v193
	ds_write_b32 v97, v197 offset:12256
	s_waitcnt lgkmcnt(7)
	v_fma_f32 v194, -v72, v193, v194
	v_fma_f32 v195, v72, v192, v195
	v_fma_f32 v194, v74, v192, v194
	v_fma_f32 v195, v74, v193, v195
	v_cvt_pk_bf16_f32 v198, v194, v195
	ds_write_b32 v97, v198 offset:12528
	s_branch .Ls5cm0_join

.Ls5cm0_join:
	v_mov_b32_e32 v120, v194
	v_mov_b32_e32 v121, v195
	s_waitcnt lgkmcnt(0)
	v_add_u32_e32 v196, v99, v93
	ds_read_b128 v[132:135], v196 offset:8448
	ds_read_b128 v[136:139], v196 offset:8512
	ds_read_b128 v[140:143], v196 offset:8576
	ds_read_b128 v[144:147], v196 offset:8640
	s_not_b32 s14, s3
	s_add_i32 s18, s2, s14
	s_and_b64 s[14:15], s[0:1], exec
	s_cselect_b32 s14, s3, s18
	s_add_i32 s3, s3, 1
	s_waitcnt lgkmcnt(3)
	v_mfma_f32_16x16x32_bf16 v[202:205], v[48:51], v[132:135], 0
	s_waitcnt lgkmcnt(2)
	v_mfma_f32_16x16x32_bf16 v[202:205], v[52:55], v[136:139], v[202:205]
	s_waitcnt lgkmcnt(1)
	v_mfma_f32_16x16x32_bf16 v[202:205], v[56:59], v[140:143], v[202:205]
	s_waitcnt lgkmcnt(0)
	v_mfma_f32_16x16x32_bf16 v[202:205], v[60:63], v[144:147], v[202:205]
	v_lshl_add_u32 v200, s14, 4, v103
	v_ashrrev_i32_e32 v201, 31, v200
	v_lshlrev_b64 v[200:201], 12, v[200:201]
	v_lshl_add_u64 v[200:201], v[78:79], 0, v[200:201]
	s_nop 3
	v_cvt_pk_bf16_f32 v202, v202, v203
	v_cvt_pk_bf16_f32 v203, v204, v205
	global_store_dwordx2 v[200:201], v[202:203], off
	s_waitcnt vmcnt(7)
	v_mfma_f32_16x16x32_bf16 v[132:135], v[4:7], v[36:39], 0
	v_mfma_f32_16x16x32_bf16 v[136:139], v[8:11], v[36:39], 0
	v_mfma_f32_16x16x32_bf16 v[140:143], v[12:15], v[36:39], 0
	v_mfma_f32_16x16x32_bf16 v[144:147], v[16:19], v[36:39], 0
	v_mfma_f32_16x16x32_bf16 v[148:151], v[20:23], v[36:39], 0
	v_mfma_f32_16x16x32_bf16 v[152:155], v[24:27], v[36:39], 0
	v_mfma_f32_16x16x32_bf16 v[156:159], v[28:31], v[36:39], 0
	v_mfma_f32_16x16x32_bf16 v[160:163], v[32:35], v[36:39], 0
	s_and_saveexec_b64 s[12:13], s[40:41]
	global_load_dwordx4 v[36:39], v[64:65], off
	s_mov_b64 exec, s[12:13]
	v_lshl_add_u64 v[64:65], v[64:65], 0, s[98:99]
	v_add_u32_e32 v196, v89, v93
	ds_write_b128 v196, v[132:135]
	ds_write_b128 v196, v[136:139] offset:64
	ds_write_b128 v196, v[140:143] offset:128
	ds_write_b128 v196, v[144:147] offset:192
	ds_write_b128 v196, v[148:151] offset:256
	ds_write_b128 v196, v[152:155] offset:320
	ds_write_b128 v196, v[156:159] offset:384
	ds_write_b128 v196, v[160:163] offset:448
	s_waitcnt lgkmcnt(0)
	s_and_b64 s[14:15], s[0:1], exec
	s_cbranch_scc0 .Ls5cm1_bwd
	ds_read_b64 v[164:165], v95
	ds_read_b64 v[166:167], v95 offset:528
	ds_read_b64 v[168:169], v95 offset:1056
	ds_read_b64 v[170:171], v95 offset:1584
	ds_read_b64 v[172:173], v95 offset:2112
	ds_read_b64 v[174:175], v95 offset:2640
	ds_read_b64 v[176:177], v95 offset:3168
	ds_read_b64 v[178:179], v95 offset:3696
	s_waitcnt lgkmcnt(7)
	v_fma_f32 v164, -v72, v121, v164
	v_fma_f32 v165, v72, v120, v165
	v_fma_f32 v164, v74, v120, v164
	v_fma_f32 v165, v74, v121, v165
	v_cvt_pk_bf16_f32 v197, v164, v165
	ds_write_b32 v97, v197 offset:8448
	ds_read_b64 v[180:181], v95 offset:4224
	s_waitcnt lgkmcnt(8)
	v_fma_f32 v166, -v72, v165, v166
	v_fma_f32 v167, v72, v164, v167
	v_fma_f32 v166, v74, v164, v166
	v_fma_f32 v167, v74, v165, v167
	v_cvt_pk_bf16_f32 v198, v166, v167
	ds_write_b32 v97, v198 offset:8720
	ds_read_b64 v[182:183], v95 offset:4752
	s_waitcnt lgkmcnt(9)
	v_fma_f32 v168, -v72, v167, v168
	v_fma_f32 v169, v72, v166, v169
	v_fma_f32 v168, v74, v166, v168
	v_fma_f32 v169, v74, v167, v169
	v_cvt_pk_bf16_f32 v197, v168, v169
	ds_write_b32 v97, v197 offset:8992
	ds_read_b64 v[184:185], v95 offset:5280
	s_waitcnt lgkmcnt(10)
	v_fma_f32 v170, -v72, v169, v170
	v_fma_f32 v171, v72, v168, v171
	v_fma_f32 v170, v74, v168, v170
	v_fma_f32 v171, v74, v169, v171
	v_cvt_pk_bf16_f32 v198, v170, v171
	ds_write_b32 v97, v198 offset:9264
	ds_read_b64 v[186:187], v95 offset:5808
	s_waitcnt lgkmcnt(11)
	v_fma_f32 v172, -v72, v171, v172
	v_fma_f32 v173, v72, v170, v173
	v_fma_f32 v172, v74, v170, v172
	v_fma_f32 v173, v74, v171, v173
	v_cvt_pk_bf16_f32 v197, v172, v173
	ds_write_b32 v97, v197 offset:9536
	ds_read_b64 v[188:189], v95 offset:6336
	s_waitcnt lgkmcnt(12)
	v_fma_f32 v174, -v72, v173, v174
	v_fma_f32 v175, v72, v172, v175
	v_fma_f32 v174, v74, v172, v174
	v_fma_f32 v175, v74, v173, v175
	v_cvt_pk_bf16_f32 v198, v174, v175
	ds_write_b32 v97, v198 offset:9808
	ds_read_b64 v[190:191], v95 offset:6864
	s_waitcnt lgkmcnt(13)
	v_fma_f32 v176, -v72, v175, v176
	v_fma_f32 v177, v72, v174, v177
	v_fma_f32 v176, v74, v174, v176
	v_fma_f32 v177, v74, v175, v177
	v_cvt_pk_bf16_f32 v197, v176, v177
	ds_write_b32 v97, v197 offset:10080
	ds_read_b64 v[192:193], v95 offset:7392
	s_waitcnt lgkmcnt(14)
	v_fma_f32 v178, -v72, v177, v178
	v_fma_f32 v179, v72, v176, v179
	v_fma_f32 v178, v74, v176, v178
	v_fma_f32 v179, v74, v177, v179
	v_cvt_pk_bf16_f32 v198, v178, v179
	ds_write_b32 v97, v198 offset:10352
	ds_read_b64 v[194:195], v95 offset:7920
	s_waitcnt lgkmcnt(14)
	v_fma_f32 v180, -v72, v179, v180
	v_fma_f32 v181, v72, v178, v181
	v_fma_f32 v180, v74, v178, v180
	v_fma_f32 v181, v74, v179, v181
	v_cvt_pk_bf16_f32 v197, v180, v181
	ds_write_b32 v97, v197 offset:10624
	s_waitcnt lgkmcnt(13)
	v_fma_f32 v182, -v72, v181, v182
	v_fma_f32 v183, v72, v180, v183
	v_fma_f32 v182, v74, v180, v182
	v_fma_f32 v183, v74, v181, v183
	v_cvt_pk_bf16_f32 v198, v182, v183
	ds_write_b32 v97, v198 offset:10896
	s_waitcnt lgkmcnt(12)
	v_fma_f32 v184, -v72, v183, v184
	v_fma_f32 v185, v72, v182, v185
	v_fma_f32 v184, v74, v182, v184
	v_fma_f32 v185, v74, v183, v185
	v_cvt_pk_bf16_f32 v197, v184, v185
	ds_write_b32 v97, v197 offset:11168
	s_waitcnt lgkmcnt(11)
	v_fma_f32 v186, -v72, v185, v186
	v_fma_f32 v187, v72, v184, v187
	v_fma_f32 v186, v74, v184, v186
	v_fma_f32 v187, v74, v185, v187
	v_cvt_pk_bf16_f32 v198, v186, v187
	ds_write_b32 v97, v198 offset:11440
	s_waitcnt lgkmcnt(10)
	v_fma_f32 v188, -v72, v187, v188
	v_fma_f32 v189, v72, v186, v189
	v_fma_f32 v188, v74, v186, v188
	v_fma_f32 v189, v74, v187, v189
	v_cvt_pk_bf16_f32 v197, v188, v189
	ds_write_b32 v97, v197 offset:11712
	s_waitcnt lgkmcnt(9)
	v_fma_f32 v190, -v72, v189, v190
	v_fma_f32 v191, v72, v188, v191
	v_fma_f32 v190, v74, v188, v190
	v_fma_f32 v191, v74, v189, v191
	v_cvt_pk_bf16_f32 v198, v190, v191
	ds_write_b32 v97, v198 offset:11984
	s_waitcnt lgkmcnt(8)
	v_fma_f32 v192, -v72, v191, v192
	v_fma_f32 v193, v72, v190, v193
	v_fma_f32 v192, v74, v190, v192
	v_fma_f32 v193, v74, v191, v193
	v_cvt_pk_bf16_f32 v197, v192, v193
	ds_write_b32 v97, v197 offset:12256
	s_waitcnt lgkmcnt(7)
	v_fma_f32 v194, -v72, v193, v194
	v_fma_f32 v195, v72, v192, v195
	v_fma_f32 v194, v74, v192, v194
	v_fma_f32 v195, v74, v193, v195
	v_cvt_pk_bf16_f32 v198, v194, v195
	ds_write_b32 v97, v198 offset:12528
	s_branch .Ls5cm1_join

.Ls5cm1_join:
	v_mov_b32_e32 v120, v194
	v_mov_b32_e32 v121, v195
	s_waitcnt lgkmcnt(0)
	v_add_u32_e32 v196, v99, v93
	ds_read_b128 v[132:135], v196 offset:8448
	ds_read_b128 v[136:139], v196 offset:8512
	ds_read_b128 v[140:143], v196 offset:8576
	ds_read_b128 v[144:147], v196 offset:8640
	s_not_b32 s14, s3
	s_add_i32 s18, s2, s14
	s_and_b64 s[14:15], s[0:1], exec
	s_cselect_b32 s14, s3, s18
	s_add_i32 s3, s3, 1
	s_waitcnt lgkmcnt(3)
	v_mfma_f32_16x16x32_bf16 v[202:205], v[48:51], v[132:135], 0
	s_waitcnt lgkmcnt(2)
	v_mfma_f32_16x16x32_bf16 v[202:205], v[52:55], v[136:139], v[202:205]
	s_waitcnt lgkmcnt(1)
	v_mfma_f32_16x16x32_bf16 v[202:205], v[56:59], v[140:143], v[202:205]
	s_waitcnt lgkmcnt(0)
	v_mfma_f32_16x16x32_bf16 v[202:205], v[60:63], v[144:147], v[202:205]
	v_lshl_add_u32 v200, s14, 4, v103
	v_ashrrev_i32_e32 v201, 31, v200
	v_lshlrev_b64 v[200:201], 12, v[200:201]
	v_lshl_add_u64 v[200:201], v[78:79], 0, v[200:201]
	s_nop 3
	v_cvt_pk_bf16_f32 v202, v202, v203
	v_cvt_pk_bf16_f32 v203, v204, v205
	global_store_dwordx2 v[200:201], v[202:203], off
	s_waitcnt vmcnt(7)
	v_mfma_f32_16x16x32_bf16 v[132:135], v[4:7], v[40:43], 0
	v_mfma_f32_16x16x32_bf16 v[136:139], v[8:11], v[40:43], 0
	v_mfma_f32_16x16x32_bf16 v[140:143], v[12:15], v[40:43], 0
	v_mfma_f32_16x16x32_bf16 v[144:147], v[16:19], v[40:43], 0
	v_mfma_f32_16x16x32_bf16 v[148:151], v[20:23], v[40:43], 0
	v_mfma_f32_16x16x32_bf16 v[152:155], v[24:27], v[40:43], 0
	v_mfma_f32_16x16x32_bf16 v[156:159], v[28:31], v[40:43], 0
	v_mfma_f32_16x16x32_bf16 v[160:163], v[32:35], v[40:43], 0
	s_and_saveexec_b64 s[12:13], s[40:41]
	global_load_dwordx4 v[40:43], v[64:65], off
	s_mov_b64 exec, s[12:13]
	v_lshl_add_u64 v[64:65], v[64:65], 0, s[98:99]
	v_add_u32_e32 v196, v89, v93
	ds_write_b128 v196, v[132:135]
	ds_write_b128 v196, v[136:139] offset:64
	ds_write_b128 v196, v[140:143] offset:128
	ds_write_b128 v196, v[144:147] offset:192
	ds_write_b128 v196, v[148:151] offset:256
	ds_write_b128 v196, v[152:155] offset:320
	ds_write_b128 v196, v[156:159] offset:384
	ds_write_b128 v196, v[160:163] offset:448
	s_waitcnt lgkmcnt(0)
	s_and_b64 s[14:15], s[0:1], exec
	s_cbranch_scc0 .Ls5cm2_bwd
	ds_read_b64 v[164:165], v95
	ds_read_b64 v[166:167], v95 offset:528
	ds_read_b64 v[168:169], v95 offset:1056
	ds_read_b64 v[170:171], v95 offset:1584
	ds_read_b64 v[172:173], v95 offset:2112
	ds_read_b64 v[174:175], v95 offset:2640
	ds_read_b64 v[176:177], v95 offset:3168
	ds_read_b64 v[178:179], v95 offset:3696
	s_waitcnt lgkmcnt(7)
	v_fma_f32 v164, -v72, v121, v164
	v_fma_f32 v165, v72, v120, v165
	v_fma_f32 v164, v74, v120, v164
	v_fma_f32 v165, v74, v121, v165
	v_cvt_pk_bf16_f32 v197, v164, v165
	ds_write_b32 v97, v197 offset:8448
	ds_read_b64 v[180:181], v95 offset:4224
	s_waitcnt lgkmcnt(8)
	v_fma_f32 v166, -v72, v165, v166
	v_fma_f32 v167, v72, v164, v167
	v_fma_f32 v166, v74, v164, v166
	v_fma_f32 v167, v74, v165, v167
	v_cvt_pk_bf16_f32 v198, v166, v167
	ds_write_b32 v97, v198 offset:8720
	ds_read_b64 v[182:183], v95 offset:4752
	s_waitcnt lgkmcnt(9)
	v_fma_f32 v168, -v72, v167, v168
	v_fma_f32 v169, v72, v166, v169
	v_fma_f32 v168, v74, v166, v168
	v_fma_f32 v169, v74, v167, v169
	v_cvt_pk_bf16_f32 v197, v168, v169
	ds_write_b32 v97, v197 offset:8992
	ds_read_b64 v[184:185], v95 offset:5280
	s_waitcnt lgkmcnt(10)
	v_fma_f32 v170, -v72, v169, v170
	v_fma_f32 v171, v72, v168, v171
	v_fma_f32 v170, v74, v168, v170
	v_fma_f32 v171, v74, v169, v171
	v_cvt_pk_bf16_f32 v198, v170, v171
	ds_write_b32 v97, v198 offset:9264
	ds_read_b64 v[186:187], v95 offset:5808
	s_waitcnt lgkmcnt(11)
	v_fma_f32 v172, -v72, v171, v172
	v_fma_f32 v173, v72, v170, v173
	v_fma_f32 v172, v74, v170, v172
	v_fma_f32 v173, v74, v171, v173
	v_cvt_pk_bf16_f32 v197, v172, v173
	ds_write_b32 v97, v197 offset:9536
	ds_read_b64 v[188:189], v95 offset:6336
	s_waitcnt lgkmcnt(12)
	v_fma_f32 v174, -v72, v173, v174
	v_fma_f32 v175, v72, v172, v175
	v_fma_f32 v174, v74, v172, v174
	v_fma_f32 v175, v74, v173, v175
	v_cvt_pk_bf16_f32 v198, v174, v175
	ds_write_b32 v97, v198 offset:9808
	ds_read_b64 v[190:191], v95 offset:6864
	s_waitcnt lgkmcnt(13)
	v_fma_f32 v176, -v72, v175, v176
	v_fma_f32 v177, v72, v174, v177
	v_fma_f32 v176, v74, v174, v176
	v_fma_f32 v177, v74, v175, v177
	v_cvt_pk_bf16_f32 v197, v176, v177
	ds_write_b32 v97, v197 offset:10080
	ds_read_b64 v[192:193], v95 offset:7392
	s_waitcnt lgkmcnt(14)
	v_fma_f32 v178, -v72, v177, v178
	v_fma_f32 v179, v72, v176, v179
	v_fma_f32 v178, v74, v176, v178
	v_fma_f32 v179, v74, v177, v179
	v_cvt_pk_bf16_f32 v198, v178, v179
	ds_write_b32 v97, v198 offset:10352
	ds_read_b64 v[194:195], v95 offset:7920
	s_waitcnt lgkmcnt(14)
	v_fma_f32 v180, -v72, v179, v180
	v_fma_f32 v181, v72, v178, v181
	v_fma_f32 v180, v74, v178, v180
	v_fma_f32 v181, v74, v179, v181
	v_cvt_pk_bf16_f32 v197, v180, v181
	ds_write_b32 v97, v197 offset:10624
	s_waitcnt lgkmcnt(13)
	v_fma_f32 v182, -v72, v181, v182
	v_fma_f32 v183, v72, v180, v183
	v_fma_f32 v182, v74, v180, v182
	v_fma_f32 v183, v74, v181, v183
	v_cvt_pk_bf16_f32 v198, v182, v183
	ds_write_b32 v97, v198 offset:10896
	s_waitcnt lgkmcnt(12)
	v_fma_f32 v184, -v72, v183, v184
	v_fma_f32 v185, v72, v182, v185
	v_fma_f32 v184, v74, v182, v184
	v_fma_f32 v185, v74, v183, v185
	v_cvt_pk_bf16_f32 v197, v184, v185
	ds_write_b32 v97, v197 offset:11168
	s_waitcnt lgkmcnt(11)
	v_fma_f32 v186, -v72, v185, v186
	v_fma_f32 v187, v72, v184, v187
	v_fma_f32 v186, v74, v184, v186
	v_fma_f32 v187, v74, v185, v187
	v_cvt_pk_bf16_f32 v198, v186, v187
	ds_write_b32 v97, v198 offset:11440
	s_waitcnt lgkmcnt(10)
	v_fma_f32 v188, -v72, v187, v188
	v_fma_f32 v189, v72, v186, v189
	v_fma_f32 v188, v74, v186, v188
	v_fma_f32 v189, v74, v187, v189
	v_cvt_pk_bf16_f32 v197, v188, v189
	ds_write_b32 v97, v197 offset:11712
	s_waitcnt lgkmcnt(9)
	v_fma_f32 v190, -v72, v189, v190
	v_fma_f32 v191, v72, v188, v191
	v_fma_f32 v190, v74, v188, v190
	v_fma_f32 v191, v74, v189, v191
	v_cvt_pk_bf16_f32 v198, v190, v191
	ds_write_b32 v97, v198 offset:11984
	s_waitcnt lgkmcnt(8)
	v_fma_f32 v192, -v72, v191, v192
	v_fma_f32 v193, v72, v190, v193
	v_fma_f32 v192, v74, v190, v192
	v_fma_f32 v193, v74, v191, v193
	v_cvt_pk_bf16_f32 v197, v192, v193
	ds_write_b32 v97, v197 offset:12256
	s_waitcnt lgkmcnt(7)
	v_fma_f32 v194, -v72, v193, v194
	v_fma_f32 v195, v72, v192, v195
	v_fma_f32 v194, v74, v192, v194
	v_fma_f32 v195, v74, v193, v195
	v_cvt_pk_bf16_f32 v198, v194, v195
	ds_write_b32 v97, v198 offset:12528
	s_branch .Ls5cm2_join

.Ls5cm2_join:
	v_mov_b32_e32 v120, v194
	v_mov_b32_e32 v121, v195
	s_waitcnt lgkmcnt(0)
	v_add_u32_e32 v196, v99, v93
	ds_read_b128 v[132:135], v196 offset:8448
	ds_read_b128 v[136:139], v196 offset:8512
	ds_read_b128 v[140:143], v196 offset:8576
	ds_read_b128 v[144:147], v196 offset:8640
	s_not_b32 s14, s3
	s_add_i32 s18, s2, s14
	s_and_b64 s[14:15], s[0:1], exec
	s_cselect_b32 s14, s3, s18
	s_add_i32 s3, s3, 1
	s_waitcnt lgkmcnt(3)
	v_mfma_f32_16x16x32_bf16 v[202:205], v[48:51], v[132:135], 0
	s_waitcnt lgkmcnt(2)
	v_mfma_f32_16x16x32_bf16 v[202:205], v[52:55], v[136:139], v[202:205]
	s_waitcnt lgkmcnt(1)
	v_mfma_f32_16x16x32_bf16 v[202:205], v[56:59], v[140:143], v[202:205]
	s_waitcnt lgkmcnt(0)
	v_mfma_f32_16x16x32_bf16 v[202:205], v[60:63], v[144:147], v[202:205]
	v_lshl_add_u32 v200, s14, 4, v103
	v_ashrrev_i32_e32 v201, 31, v200
	v_lshlrev_b64 v[200:201], 12, v[200:201]
	v_lshl_add_u64 v[200:201], v[78:79], 0, v[200:201]
	s_nop 3
	v_cvt_pk_bf16_f32 v202, v202, v203
	v_cvt_pk_bf16_f32 v203, v204, v205
	global_store_dwordx2 v[200:201], v[202:203], off
	s_waitcnt vmcnt(7)
	v_mfma_f32_16x16x32_bf16 v[132:135], v[4:7], v[44:47], 0
	v_mfma_f32_16x16x32_bf16 v[136:139], v[8:11], v[44:47], 0
	v_mfma_f32_16x16x32_bf16 v[140:143], v[12:15], v[44:47], 0
	v_mfma_f32_16x16x32_bf16 v[144:147], v[16:19], v[44:47], 0
	v_mfma_f32_16x16x32_bf16 v[148:151], v[20:23], v[44:47], 0
	v_mfma_f32_16x16x32_bf16 v[152:155], v[24:27], v[44:47], 0
	v_mfma_f32_16x16x32_bf16 v[156:159], v[28:31], v[44:47], 0
	v_mfma_f32_16x16x32_bf16 v[160:163], v[32:35], v[44:47], 0
	s_and_saveexec_b64 s[12:13], s[40:41]
	global_load_dwordx4 v[44:47], v[64:65], off
	s_mov_b64 exec, s[12:13]
	v_lshl_add_u64 v[64:65], v[64:65], 0, s[98:99]
	v_add_u32_e32 v196, v89, v93
	ds_write_b128 v196, v[132:135]
	ds_write_b128 v196, v[136:139] offset:64
	ds_write_b128 v196, v[140:143] offset:128
	ds_write_b128 v196, v[144:147] offset:192
	ds_write_b128 v196, v[148:151] offset:256
	ds_write_b128 v196, v[152:155] offset:320
	ds_write_b128 v196, v[156:159] offset:384
	ds_write_b128 v196, v[160:163] offset:448
	s_waitcnt lgkmcnt(0)
	s_and_b64 s[14:15], s[0:1], exec
	s_cbranch_scc0 .Ls5cm3_bwd
	ds_read_b64 v[164:165], v95
	ds_read_b64 v[166:167], v95 offset:528
	ds_read_b64 v[168:169], v95 offset:1056
	ds_read_b64 v[170:171], v95 offset:1584
	ds_read_b64 v[172:173], v95 offset:2112
	ds_read_b64 v[174:175], v95 offset:2640
	ds_read_b64 v[176:177], v95 offset:3168
	ds_read_b64 v[178:179], v95 offset:3696
	s_waitcnt lgkmcnt(7)
	v_fma_f32 v164, -v72, v121, v164
	v_fma_f32 v165, v72, v120, v165
	v_fma_f32 v164, v74, v120, v164
	v_fma_f32 v165, v74, v121, v165
	v_cvt_pk_bf16_f32 v197, v164, v165
	ds_write_b32 v97, v197 offset:8448
	ds_read_b64 v[180:181], v95 offset:4224
	s_waitcnt lgkmcnt(8)
	v_fma_f32 v166, -v72, v165, v166
	v_fma_f32 v167, v72, v164, v167
	v_fma_f32 v166, v74, v164, v166
	v_fma_f32 v167, v74, v165, v167
	v_cvt_pk_bf16_f32 v198, v166, v167
	ds_write_b32 v97, v198 offset:8720
	ds_read_b64 v[182:183], v95 offset:4752
	s_waitcnt lgkmcnt(9)
	v_fma_f32 v168, -v72, v167, v168
	v_fma_f32 v169, v72, v166, v169
	v_fma_f32 v168, v74, v166, v168
	v_fma_f32 v169, v74, v167, v169
	v_cvt_pk_bf16_f32 v197, v168, v169
	ds_write_b32 v97, v197 offset:8992
	ds_read_b64 v[184:185], v95 offset:5280
	s_waitcnt lgkmcnt(10)
	v_fma_f32 v170, -v72, v169, v170
	v_fma_f32 v171, v72, v168, v171
	v_fma_f32 v170, v74, v168, v170
	v_fma_f32 v171, v74, v169, v171
	v_cvt_pk_bf16_f32 v198, v170, v171
	ds_write_b32 v97, v198 offset:9264
	ds_read_b64 v[186:187], v95 offset:5808
	s_waitcnt lgkmcnt(11)
	v_fma_f32 v172, -v72, v171, v172
	v_fma_f32 v173, v72, v170, v173
	v_fma_f32 v172, v74, v170, v172
	v_fma_f32 v173, v74, v171, v173
	v_cvt_pk_bf16_f32 v197, v172, v173
	ds_write_b32 v97, v197 offset:9536
	ds_read_b64 v[188:189], v95 offset:6336
	s_waitcnt lgkmcnt(12)
	v_fma_f32 v174, -v72, v173, v174
	v_fma_f32 v175, v72, v172, v175
	v_fma_f32 v174, v74, v172, v174
	v_fma_f32 v175, v74, v173, v175
	v_cvt_pk_bf16_f32 v198, v174, v175
	ds_write_b32 v97, v198 offset:9808
	ds_read_b64 v[190:191], v95 offset:6864
	s_waitcnt lgkmcnt(13)
	v_fma_f32 v176, -v72, v175, v176
	v_fma_f32 v177, v72, v174, v177
	v_fma_f32 v176, v74, v174, v176
	v_fma_f32 v177, v74, v175, v177
	v_cvt_pk_bf16_f32 v197, v176, v177
	ds_write_b32 v97, v197 offset:10080
	ds_read_b64 v[192:193], v95 offset:7392
	s_waitcnt lgkmcnt(14)
	v_fma_f32 v178, -v72, v177, v178
	v_fma_f32 v179, v72, v176, v179
	v_fma_f32 v178, v74, v176, v178
	v_fma_f32 v179, v74, v177, v179
	v_cvt_pk_bf16_f32 v198, v178, v179
	ds_write_b32 v97, v198 offset:10352
	ds_read_b64 v[194:195], v95 offset:7920
	s_waitcnt lgkmcnt(14)
	v_fma_f32 v180, -v72, v179, v180
	v_fma_f32 v181, v72, v178, v181
	v_fma_f32 v180, v74, v178, v180
	v_fma_f32 v181, v74, v179, v181
	v_cvt_pk_bf16_f32 v197, v180, v181
	ds_write_b32 v97, v197 offset:10624
	s_waitcnt lgkmcnt(13)
	v_fma_f32 v182, -v72, v181, v182
	v_fma_f32 v183, v72, v180, v183
	v_fma_f32 v182, v74, v180, v182
	v_fma_f32 v183, v74, v181, v183
	v_cvt_pk_bf16_f32 v198, v182, v183
	ds_write_b32 v97, v198 offset:10896
	s_waitcnt lgkmcnt(12)
	v_fma_f32 v184, -v72, v183, v184
	v_fma_f32 v185, v72, v182, v185
	v_fma_f32 v184, v74, v182, v184
	v_fma_f32 v185, v74, v183, v185
	v_cvt_pk_bf16_f32 v197, v184, v185
	ds_write_b32 v97, v197 offset:11168
	s_waitcnt lgkmcnt(11)
	v_fma_f32 v186, -v72, v185, v186
	v_fma_f32 v187, v72, v184, v187
	v_fma_f32 v186, v74, v184, v186
	v_fma_f32 v187, v74, v185, v187
	v_cvt_pk_bf16_f32 v198, v186, v187
	ds_write_b32 v97, v198 offset:11440
	s_waitcnt lgkmcnt(10)
	v_fma_f32 v188, -v72, v187, v188
	v_fma_f32 v189, v72, v186, v189
	v_fma_f32 v188, v74, v186, v188
	v_fma_f32 v189, v74, v187, v189
	v_cvt_pk_bf16_f32 v197, v188, v189
	ds_write_b32 v97, v197 offset:11712
	s_waitcnt lgkmcnt(9)
	v_fma_f32 v190, -v72, v189, v190
	v_fma_f32 v191, v72, v188, v191
	v_fma_f32 v190, v74, v188, v190
	v_fma_f32 v191, v74, v189, v191
	v_cvt_pk_bf16_f32 v198, v190, v191
	ds_write_b32 v97, v198 offset:11984
	s_waitcnt lgkmcnt(8)
	v_fma_f32 v192, -v72, v191, v192
	v_fma_f32 v193, v72, v190, v193
	v_fma_f32 v192, v74, v190, v192
	v_fma_f32 v193, v74, v191, v193
	v_cvt_pk_bf16_f32 v197, v192, v193
	ds_write_b32 v97, v197 offset:12256
	s_waitcnt lgkmcnt(7)
	v_fma_f32 v194, -v72, v193, v194
	v_fma_f32 v195, v72, v192, v195
	v_fma_f32 v194, v74, v192, v194
	v_fma_f32 v195, v74, v193, v195
	v_cvt_pk_bf16_f32 v198, v194, v195
	ds_write_b32 v97, v198 offset:12528
	s_branch .Ls5cm3_join

.Ls5cm3_join:
	v_mov_b32_e32 v120, v194
	v_mov_b32_e32 v121, v195
	s_waitcnt lgkmcnt(0)
	v_add_u32_e32 v196, v99, v93
	ds_read_b128 v[132:135], v196 offset:8448
	ds_read_b128 v[136:139], v196 offset:8512
	ds_read_b128 v[140:143], v196 offset:8576
	ds_read_b128 v[144:147], v196 offset:8640
	s_not_b32 s14, s3
	s_add_i32 s18, s2, s14
	s_and_b64 s[14:15], s[0:1], exec
	s_cselect_b32 s14, s3, s18
	s_add_i32 s3, s3, 1
	s_waitcnt lgkmcnt(3)
	v_mfma_f32_16x16x32_bf16 v[202:205], v[48:51], v[132:135], 0
	s_waitcnt lgkmcnt(2)
	v_mfma_f32_16x16x32_bf16 v[202:205], v[52:55], v[136:139], v[202:205]
	s_waitcnt lgkmcnt(1)
	v_mfma_f32_16x16x32_bf16 v[202:205], v[56:59], v[140:143], v[202:205]
	s_waitcnt lgkmcnt(0)
	v_mfma_f32_16x16x32_bf16 v[202:205], v[60:63], v[144:147], v[202:205]
	v_lshl_add_u32 v200, s14, 4, v103
	v_ashrrev_i32_e32 v201, 31, v200
	v_lshlrev_b64 v[200:201], 12, v[200:201]
	v_lshl_add_u64 v[200:201], v[78:79], 0, v[200:201]
	s_nop 3
	v_cvt_pk_bf16_f32 v202, v202, v203
	v_cvt_pk_bf16_f32 v203, v204, v205
	global_store_dwordx2 v[200:201], v[202:203], off
	s_add_i32 s18, s3, 4
	s_cmp_lt_u32 s18, s2
	s_cbranch_scc1 .Ls5c_main
	s_waitcnt vmcnt(7)
	v_mfma_f32_16x16x32_bf16 v[132:135], v[4:7], v[68:71], 0
	v_mfma_f32_16x16x32_bf16 v[136:139], v[8:11], v[68:71], 0
	v_mfma_f32_16x16x32_bf16 v[140:143], v[12:15], v[68:71], 0
	v_mfma_f32_16x16x32_bf16 v[144:147], v[16:19], v[68:71], 0
	v_mfma_f32_16x16x32_bf16 v[148:151], v[20:23], v[68:71], 0
	v_mfma_f32_16x16x32_bf16 v[152:155], v[24:27], v[68:71], 0
	v_mfma_f32_16x16x32_bf16 v[156:159], v[28:31], v[68:71], 0
	v_mfma_f32_16x16x32_bf16 v[160:163], v[32:35], v[68:71], 0
	v_add_u32_e32 v196, v89, v93
	ds_write_b128 v196, v[132:135]
	ds_write_b128 v196, v[136:139] offset:64
	ds_write_b128 v196, v[140:143] offset:128
	ds_write_b128 v196, v[144:147] offset:192
	ds_write_b128 v196, v[148:151] offset:256
	ds_write_b128 v196, v[152:155] offset:320
	ds_write_b128 v196, v[156:159] offset:384
	ds_write_b128 v196, v[160:163] offset:448
	s_waitcnt lgkmcnt(0)
	s_and_b64 s[14:15], s[0:1], exec
	s_cbranch_scc0 .Ls5ct0_bwd
	ds_read_b64 v[164:165], v95
	ds_read_b64 v[166:167], v95 offset:528
	ds_read_b64 v[168:169], v95 offset:1056
	ds_read_b64 v[170:171], v95 offset:1584
	ds_read_b64 v[172:173], v95 offset:2112
	ds_read_b64 v[174:175], v95 offset:2640
	ds_read_b64 v[176:177], v95 offset:3168
	ds_read_b64 v[178:179], v95 offset:3696
	s_waitcnt lgkmcnt(7)
	v_fma_f32 v164, -v72, v121, v164
	v_fma_f32 v165, v72, v120, v165
	v_fma_f32 v164, v74, v120, v164
	v_fma_f32 v165, v74, v121, v165
	v_cvt_pk_bf16_f32 v197, v164, v165
	ds_write_b32 v97, v197 offset:8448
	ds_read_b64 v[180:181], v95 offset:4224
	s_waitcnt lgkmcnt(8)
	v_fma_f32 v166, -v72, v165, v166
	v_fma_f32 v167, v72, v164, v167
	v_fma_f32 v166, v74, v164, v166
	v_fma_f32 v167, v74, v165, v167
	v_cvt_pk_bf16_f32 v198, v166, v167
	ds_write_b32 v97, v198 offset:8720
	ds_read_b64 v[182:183], v95 offset:4752
	s_waitcnt lgkmcnt(9)
	v_fma_f32 v168, -v72, v167, v168
	v_fma_f32 v169, v72, v166, v169
	v_fma_f32 v168, v74, v166, v168
	v_fma_f32 v169, v74, v167, v169
	v_cvt_pk_bf16_f32 v197, v168, v169
	ds_write_b32 v97, v197 offset:8992
	ds_read_b64 v[184:185], v95 offset:5280
	s_waitcnt lgkmcnt(10)
	v_fma_f32 v170, -v72, v169, v170
	v_fma_f32 v171, v72, v168, v171
	v_fma_f32 v170, v74, v168, v170
	v_fma_f32 v171, v74, v169, v171
	v_cvt_pk_bf16_f32 v198, v170, v171
	ds_write_b32 v97, v198 offset:9264
	ds_read_b64 v[186:187], v95 offset:5808
	s_waitcnt lgkmcnt(11)
	v_fma_f32 v172, -v72, v171, v172
	v_fma_f32 v173, v72, v170, v173
	v_fma_f32 v172, v74, v170, v172
	v_fma_f32 v173, v74, v171, v173
	v_cvt_pk_bf16_f32 v197, v172, v173
	ds_write_b32 v97, v197 offset:9536
	ds_read_b64 v[188:189], v95 offset:6336
	s_waitcnt lgkmcnt(12)
	v_fma_f32 v174, -v72, v173, v174
	v_fma_f32 v175, v72, v172, v175
	v_fma_f32 v174, v74, v172, v174
	v_fma_f32 v175, v74, v173, v175
	v_cvt_pk_bf16_f32 v198, v174, v175
	ds_write_b32 v97, v198 offset:9808
	ds_read_b64 v[190:191], v95 offset:6864
	s_waitcnt lgkmcnt(13)
	v_fma_f32 v176, -v72, v175, v176
	v_fma_f32 v177, v72, v174, v177
	v_fma_f32 v176, v74, v174, v176
	v_fma_f32 v177, v74, v175, v177
	v_cvt_pk_bf16_f32 v197, v176, v177
	ds_write_b32 v97, v197 offset:10080
	ds_read_b64 v[192:193], v95 offset:7392
	s_waitcnt lgkmcnt(14)
	v_fma_f32 v178, -v72, v177, v178
	v_fma_f32 v179, v72, v176, v179
	v_fma_f32 v178, v74, v176, v178
	v_fma_f32 v179, v74, v177, v179
	v_cvt_pk_bf16_f32 v198, v178, v179
	ds_write_b32 v97, v198 offset:10352
	ds_read_b64 v[194:195], v95 offset:7920
	s_waitcnt lgkmcnt(14)
	v_fma_f32 v180, -v72, v179, v180
	v_fma_f32 v181, v72, v178, v181
	v_fma_f32 v180, v74, v178, v180
	v_fma_f32 v181, v74, v179, v181
	v_cvt_pk_bf16_f32 v197, v180, v181
	ds_write_b32 v97, v197 offset:10624
	s_waitcnt lgkmcnt(13)
	v_fma_f32 v182, -v72, v181, v182
	v_fma_f32 v183, v72, v180, v183
	v_fma_f32 v182, v74, v180, v182
	v_fma_f32 v183, v74, v181, v183
	v_cvt_pk_bf16_f32 v198, v182, v183
	ds_write_b32 v97, v198 offset:10896
	s_waitcnt lgkmcnt(12)
	v_fma_f32 v184, -v72, v183, v184
	v_fma_f32 v185, v72, v182, v185
	v_fma_f32 v184, v74, v182, v184
	v_fma_f32 v185, v74, v183, v185
	v_cvt_pk_bf16_f32 v197, v184, v185
	ds_write_b32 v97, v197 offset:11168
	s_waitcnt lgkmcnt(11)
	v_fma_f32 v186, -v72, v185, v186
	v_fma_f32 v187, v72, v184, v187
	v_fma_f32 v186, v74, v184, v186
	v_fma_f32 v187, v74, v185, v187
	v_cvt_pk_bf16_f32 v198, v186, v187
	ds_write_b32 v97, v198 offset:11440
	s_waitcnt lgkmcnt(10)
	v_fma_f32 v188, -v72, v187, v188
	v_fma_f32 v189, v72, v186, v189
	v_fma_f32 v188, v74, v186, v188
	v_fma_f32 v189, v74, v187, v189
	v_cvt_pk_bf16_f32 v197, v188, v189
	ds_write_b32 v97, v197 offset:11712
	s_waitcnt lgkmcnt(9)
	v_fma_f32 v190, -v72, v189, v190
	v_fma_f32 v191, v72, v188, v191
	v_fma_f32 v190, v74, v188, v190
	v_fma_f32 v191, v74, v189, v191
	v_cvt_pk_bf16_f32 v198, v190, v191
	ds_write_b32 v97, v198 offset:11984
	s_waitcnt lgkmcnt(8)
	v_fma_f32 v192, -v72, v191, v192
	v_fma_f32 v193, v72, v190, v193
	v_fma_f32 v192, v74, v190, v192
	v_fma_f32 v193, v74, v191, v193
	v_cvt_pk_bf16_f32 v197, v192, v193
	ds_write_b32 v97, v197 offset:12256
	s_waitcnt lgkmcnt(7)
	v_fma_f32 v194, -v72, v193, v194
	v_fma_f32 v195, v72, v192, v195
	v_fma_f32 v194, v74, v192, v194
	v_fma_f32 v195, v74, v193, v195
	v_cvt_pk_bf16_f32 v198, v194, v195
	ds_write_b32 v97, v198 offset:12528
	s_branch .Ls5ct0_join

.Ls5ct0_join:
	v_mov_b32_e32 v120, v194
	v_mov_b32_e32 v121, v195
	s_waitcnt lgkmcnt(0)
	v_add_u32_e32 v196, v99, v93
	ds_read_b128 v[132:135], v196 offset:8448
	ds_read_b128 v[136:139], v196 offset:8512
	ds_read_b128 v[140:143], v196 offset:8576
	ds_read_b128 v[144:147], v196 offset:8640
	s_not_b32 s14, s3
	s_add_i32 s18, s2, s14
	s_and_b64 s[14:15], s[0:1], exec
	s_cselect_b32 s14, s3, s18
	s_add_i32 s3, s3, 1
	s_waitcnt lgkmcnt(3)
	v_mfma_f32_16x16x32_bf16 v[202:205], v[48:51], v[132:135], 0
	s_waitcnt lgkmcnt(2)
	v_mfma_f32_16x16x32_bf16 v[202:205], v[52:55], v[136:139], v[202:205]
	s_waitcnt lgkmcnt(1)
	v_mfma_f32_16x16x32_bf16 v[202:205], v[56:59], v[140:143], v[202:205]
	s_waitcnt lgkmcnt(0)
	v_mfma_f32_16x16x32_bf16 v[202:205], v[60:63], v[144:147], v[202:205]
	v_lshl_add_u32 v200, s14, 4, v103
	v_ashrrev_i32_e32 v201, 31, v200
	v_lshlrev_b64 v[200:201], 12, v[200:201]
	v_lshl_add_u64 v[200:201], v[78:79], 0, v[200:201]
	s_nop 3
	v_cvt_pk_bf16_f32 v202, v202, v203
	v_cvt_pk_bf16_f32 v203, v204, v205
	global_store_dwordx2 v[200:201], v[202:203], off
	s_waitcnt vmcnt(6)
	v_mfma_f32_16x16x32_bf16 v[132:135], v[4:7], v[36:39], 0
	v_mfma_f32_16x16x32_bf16 v[136:139], v[8:11], v[36:39], 0
	v_mfma_f32_16x16x32_bf16 v[140:143], v[12:15], v[36:39], 0
	v_mfma_f32_16x16x32_bf16 v[144:147], v[16:19], v[36:39], 0
	v_mfma_f32_16x16x32_bf16 v[148:151], v[20:23], v[36:39], 0
	v_mfma_f32_16x16x32_bf16 v[152:155], v[24:27], v[36:39], 0
	v_mfma_f32_16x16x32_bf16 v[156:159], v[28:31], v[36:39], 0
	v_mfma_f32_16x16x32_bf16 v[160:163], v[32:35], v[36:39], 0
	v_add_u32_e32 v196, v89, v93
	ds_write_b128 v196, v[132:135]
	ds_write_b128 v196, v[136:139] offset:64
	ds_write_b128 v196, v[140:143] offset:128
	ds_write_b128 v196, v[144:147] offset:192
	ds_write_b128 v196, v[148:151] offset:256
	ds_write_b128 v196, v[152:155] offset:320
	ds_write_b128 v196, v[156:159] offset:384
	ds_write_b128 v196, v[160:163] offset:448
	s_waitcnt lgkmcnt(0)
	s_and_b64 s[14:15], s[0:1], exec
	s_cbranch_scc0 .Ls5ct1_bwd
	ds_read_b64 v[164:165], v95
	ds_read_b64 v[166:167], v95 offset:528
	ds_read_b64 v[168:169], v95 offset:1056
	ds_read_b64 v[170:171], v95 offset:1584
	ds_read_b64 v[172:173], v95 offset:2112
	ds_read_b64 v[174:175], v95 offset:2640
	ds_read_b64 v[176:177], v95 offset:3168
	ds_read_b64 v[178:179], v95 offset:3696
	s_waitcnt lgkmcnt(7)
	v_fma_f32 v164, -v72, v121, v164
	v_fma_f32 v165, v72, v120, v165
	v_fma_f32 v164, v74, v120, v164
	v_fma_f32 v165, v74, v121, v165
	v_cvt_pk_bf16_f32 v197, v164, v165
	ds_write_b32 v97, v197 offset:8448
	ds_read_b64 v[180:181], v95 offset:4224
	s_waitcnt lgkmcnt(8)
	v_fma_f32 v166, -v72, v165, v166
	v_fma_f32 v167, v72, v164, v167
	v_fma_f32 v166, v74, v164, v166
	v_fma_f32 v167, v74, v165, v167
	v_cvt_pk_bf16_f32 v198, v166, v167
	ds_write_b32 v97, v198 offset:8720
	ds_read_b64 v[182:183], v95 offset:4752
	s_waitcnt lgkmcnt(9)
	v_fma_f32 v168, -v72, v167, v168
	v_fma_f32 v169, v72, v166, v169
	v_fma_f32 v168, v74, v166, v168
	v_fma_f32 v169, v74, v167, v169
	v_cvt_pk_bf16_f32 v197, v168, v169
	ds_write_b32 v97, v197 offset:8992
	ds_read_b64 v[184:185], v95 offset:5280
	s_waitcnt lgkmcnt(10)
	v_fma_f32 v170, -v72, v169, v170
	v_fma_f32 v171, v72, v168, v171
	v_fma_f32 v170, v74, v168, v170
	v_fma_f32 v171, v74, v169, v171
	v_cvt_pk_bf16_f32 v198, v170, v171
	ds_write_b32 v97, v198 offset:9264
	ds_read_b64 v[186:187], v95 offset:5808
	s_waitcnt lgkmcnt(11)
	v_fma_f32 v172, -v72, v171, v172
	v_fma_f32 v173, v72, v170, v173
	v_fma_f32 v172, v74, v170, v172
	v_fma_f32 v173, v74, v171, v173
	v_cvt_pk_bf16_f32 v197, v172, v173
	ds_write_b32 v97, v197 offset:9536
	ds_read_b64 v[188:189], v95 offset:6336
	s_waitcnt lgkmcnt(12)
	v_fma_f32 v174, -v72, v173, v174
	v_fma_f32 v175, v72, v172, v175
	v_fma_f32 v174, v74, v172, v174
	v_fma_f32 v175, v74, v173, v175
	v_cvt_pk_bf16_f32 v198, v174, v175
	ds_write_b32 v97, v198 offset:9808
	ds_read_b64 v[190:191], v95 offset:6864
	s_waitcnt lgkmcnt(13)
	v_fma_f32 v176, -v72, v175, v176
	v_fma_f32 v177, v72, v174, v177
	v_fma_f32 v176, v74, v174, v176
	v_fma_f32 v177, v74, v175, v177
	v_cvt_pk_bf16_f32 v197, v176, v177
	ds_write_b32 v97, v197 offset:10080
	ds_read_b64 v[192:193], v95 offset:7392
	s_waitcnt lgkmcnt(14)
	v_fma_f32 v178, -v72, v177, v178
	v_fma_f32 v179, v72, v176, v179
	v_fma_f32 v178, v74, v176, v178
	v_fma_f32 v179, v74, v177, v179
	v_cvt_pk_bf16_f32 v198, v178, v179
	ds_write_b32 v97, v198 offset:10352
	ds_read_b64 v[194:195], v95 offset:7920
	s_waitcnt lgkmcnt(14)
	v_fma_f32 v180, -v72, v179, v180
	v_fma_f32 v181, v72, v178, v181
	v_fma_f32 v180, v74, v178, v180
	v_fma_f32 v181, v74, v179, v181
	v_cvt_pk_bf16_f32 v197, v180, v181
	ds_write_b32 v97, v197 offset:10624
	s_waitcnt lgkmcnt(13)
	v_fma_f32 v182, -v72, v181, v182
	v_fma_f32 v183, v72, v180, v183
	v_fma_f32 v182, v74, v180, v182
	v_fma_f32 v183, v74, v181, v183
	v_cvt_pk_bf16_f32 v198, v182, v183
	ds_write_b32 v97, v198 offset:10896
	s_waitcnt lgkmcnt(12)
	v_fma_f32 v184, -v72, v183, v184
	v_fma_f32 v185, v72, v182, v185
	v_fma_f32 v184, v74, v182, v184
	v_fma_f32 v185, v74, v183, v185
	v_cvt_pk_bf16_f32 v197, v184, v185
	ds_write_b32 v97, v197 offset:11168
	s_waitcnt lgkmcnt(11)
	v_fma_f32 v186, -v72, v185, v186
	v_fma_f32 v187, v72, v184, v187
	v_fma_f32 v186, v74, v184, v186
	v_fma_f32 v187, v74, v185, v187
	v_cvt_pk_bf16_f32 v198, v186, v187
	ds_write_b32 v97, v198 offset:11440
	s_waitcnt lgkmcnt(10)
	v_fma_f32 v188, -v72, v187, v188
	v_fma_f32 v189, v72, v186, v189
	v_fma_f32 v188, v74, v186, v188
	v_fma_f32 v189, v74, v187, v189
	v_cvt_pk_bf16_f32 v197, v188, v189
	ds_write_b32 v97, v197 offset:11712
	s_waitcnt lgkmcnt(9)
	v_fma_f32 v190, -v72, v189, v190
	v_fma_f32 v191, v72, v188, v191
	v_fma_f32 v190, v74, v188, v190
	v_fma_f32 v191, v74, v189, v191
	v_cvt_pk_bf16_f32 v198, v190, v191
	ds_write_b32 v97, v198 offset:11984
	s_waitcnt lgkmcnt(8)
	v_fma_f32 v192, -v72, v191, v192
	v_fma_f32 v193, v72, v190, v193
	v_fma_f32 v192, v74, v190, v192
	v_fma_f32 v193, v74, v191, v193
	v_cvt_pk_bf16_f32 v197, v192, v193
	ds_write_b32 v97, v197 offset:12256
	s_waitcnt lgkmcnt(7)
	v_fma_f32 v194, -v72, v193, v194
	v_fma_f32 v195, v72, v192, v195
	v_fma_f32 v194, v74, v192, v194
	v_fma_f32 v195, v74, v193, v195
	v_cvt_pk_bf16_f32 v198, v194, v195
	ds_write_b32 v97, v198 offset:12528
	s_branch .Ls5ct1_join

.Ls5ct1_join:
	v_mov_b32_e32 v120, v194
	v_mov_b32_e32 v121, v195
	s_waitcnt lgkmcnt(0)
	v_add_u32_e32 v196, v99, v93
	ds_read_b128 v[132:135], v196 offset:8448
	ds_read_b128 v[136:139], v196 offset:8512
	ds_read_b128 v[140:143], v196 offset:8576
	ds_read_b128 v[144:147], v196 offset:8640
	s_not_b32 s14, s3
	s_add_i32 s18, s2, s14
	s_and_b64 s[14:15], s[0:1], exec
	s_cselect_b32 s14, s3, s18
	s_add_i32 s3, s3, 1
	s_waitcnt lgkmcnt(3)
	v_mfma_f32_16x16x32_bf16 v[202:205], v[48:51], v[132:135], 0
	s_waitcnt lgkmcnt(2)
	v_mfma_f32_16x16x32_bf16 v[202:205], v[52:55], v[136:139], v[202:205]
	s_waitcnt lgkmcnt(1)
	v_mfma_f32_16x16x32_bf16 v[202:205], v[56:59], v[140:143], v[202:205]
	s_waitcnt lgkmcnt(0)
	v_mfma_f32_16x16x32_bf16 v[202:205], v[60:63], v[144:147], v[202:205]
	v_lshl_add_u32 v200, s14, 4, v103
	v_ashrrev_i32_e32 v201, 31, v200
	v_lshlrev_b64 v[200:201], 12, v[200:201]
	v_lshl_add_u64 v[200:201], v[78:79], 0, v[200:201]
	s_nop 3
	v_cvt_pk_bf16_f32 v202, v202, v203
	v_cvt_pk_bf16_f32 v203, v204, v205
	global_store_dwordx2 v[200:201], v[202:203], off
	s_waitcnt vmcnt(5)
	v_mfma_f32_16x16x32_bf16 v[132:135], v[4:7], v[40:43], 0
	v_mfma_f32_16x16x32_bf16 v[136:139], v[8:11], v[40:43], 0
	v_mfma_f32_16x16x32_bf16 v[140:143], v[12:15], v[40:43], 0
	v_mfma_f32_16x16x32_bf16 v[144:147], v[16:19], v[40:43], 0
	v_mfma_f32_16x16x32_bf16 v[148:151], v[20:23], v[40:43], 0
	v_mfma_f32_16x16x32_bf16 v[152:155], v[24:27], v[40:43], 0
	v_mfma_f32_16x16x32_bf16 v[156:159], v[28:31], v[40:43], 0
	v_mfma_f32_16x16x32_bf16 v[160:163], v[32:35], v[40:43], 0
	v_add_u32_e32 v196, v89, v93
	ds_write_b128 v196, v[132:135]
	ds_write_b128 v196, v[136:139] offset:64
	ds_write_b128 v196, v[140:143] offset:128
	ds_write_b128 v196, v[144:147] offset:192
	ds_write_b128 v196, v[148:151] offset:256
	ds_write_b128 v196, v[152:155] offset:320
	ds_write_b128 v196, v[156:159] offset:384
	ds_write_b128 v196, v[160:163] offset:448
	s_waitcnt lgkmcnt(0)
	s_and_b64 s[14:15], s[0:1], exec
	s_cbranch_scc0 .Ls5ct2_bwd
	ds_read_b64 v[164:165], v95
	ds_read_b64 v[166:167], v95 offset:528
	ds_read_b64 v[168:169], v95 offset:1056
	ds_read_b64 v[170:171], v95 offset:1584
	ds_read_b64 v[172:173], v95 offset:2112
	ds_read_b64 v[174:175], v95 offset:2640
	ds_read_b64 v[176:177], v95 offset:3168
	ds_read_b64 v[178:179], v95 offset:3696
	s_waitcnt lgkmcnt(7)
	v_fma_f32 v164, -v72, v121, v164
	v_fma_f32 v165, v72, v120, v165
	v_fma_f32 v164, v74, v120, v164
	v_fma_f32 v165, v74, v121, v165
	v_cvt_pk_bf16_f32 v197, v164, v165
	ds_write_b32 v97, v197 offset:8448
	ds_read_b64 v[180:181], v95 offset:4224
	s_waitcnt lgkmcnt(8)
	v_fma_f32 v166, -v72, v165, v166
	v_fma_f32 v167, v72, v164, v167
	v_fma_f32 v166, v74, v164, v166
	v_fma_f32 v167, v74, v165, v167
	v_cvt_pk_bf16_f32 v198, v166, v167
	ds_write_b32 v97, v198 offset:8720
	ds_read_b64 v[182:183], v95 offset:4752
	s_waitcnt lgkmcnt(9)
	v_fma_f32 v168, -v72, v167, v168
	v_fma_f32 v169, v72, v166, v169
	v_fma_f32 v168, v74, v166, v168
	v_fma_f32 v169, v74, v167, v169
	v_cvt_pk_bf16_f32 v197, v168, v169
	ds_write_b32 v97, v197 offset:8992
	ds_read_b64 v[184:185], v95 offset:5280
	s_waitcnt lgkmcnt(10)
	v_fma_f32 v170, -v72, v169, v170
	v_fma_f32 v171, v72, v168, v171
	v_fma_f32 v170, v74, v168, v170
	v_fma_f32 v171, v74, v169, v171
	v_cvt_pk_bf16_f32 v198, v170, v171
	ds_write_b32 v97, v198 offset:9264
	ds_read_b64 v[186:187], v95 offset:5808
	s_waitcnt lgkmcnt(11)
	v_fma_f32 v172, -v72, v171, v172
	v_fma_f32 v173, v72, v170, v173
	v_fma_f32 v172, v74, v170, v172
	v_fma_f32 v173, v74, v171, v173
	v_cvt_pk_bf16_f32 v197, v172, v173
	ds_write_b32 v97, v197 offset:9536
	ds_read_b64 v[188:189], v95 offset:6336
	s_waitcnt lgkmcnt(12)
	v_fma_f32 v174, -v72, v173, v174
	v_fma_f32 v175, v72, v172, v175
	v_fma_f32 v174, v74, v172, v174
	v_fma_f32 v175, v74, v173, v175
	v_cvt_pk_bf16_f32 v198, v174, v175
	ds_write_b32 v97, v198 offset:9808
	ds_read_b64 v[190:191], v95 offset:6864
	s_waitcnt lgkmcnt(13)
	v_fma_f32 v176, -v72, v175, v176
	v_fma_f32 v177, v72, v174, v177
	v_fma_f32 v176, v74, v174, v176
	v_fma_f32 v177, v74, v175, v177
	v_cvt_pk_bf16_f32 v197, v176, v177
	ds_write_b32 v97, v197 offset:10080
	ds_read_b64 v[192:193], v95 offset:7392
	s_waitcnt lgkmcnt(14)
	v_fma_f32 v178, -v72, v177, v178
	v_fma_f32 v179, v72, v176, v179
	v_fma_f32 v178, v74, v176, v178
	v_fma_f32 v179, v74, v177, v179
	v_cvt_pk_bf16_f32 v198, v178, v179
	ds_write_b32 v97, v198 offset:10352
	ds_read_b64 v[194:195], v95 offset:7920
	s_waitcnt lgkmcnt(14)
	v_fma_f32 v180, -v72, v179, v180
	v_fma_f32 v181, v72, v178, v181
	v_fma_f32 v180, v74, v178, v180
	v_fma_f32 v181, v74, v179, v181
	v_cvt_pk_bf16_f32 v197, v180, v181
	ds_write_b32 v97, v197 offset:10624
	s_waitcnt lgkmcnt(13)
	v_fma_f32 v182, -v72, v181, v182
	v_fma_f32 v183, v72, v180, v183
	v_fma_f32 v182, v74, v180, v182
	v_fma_f32 v183, v74, v181, v183
	v_cvt_pk_bf16_f32 v198, v182, v183
	ds_write_b32 v97, v198 offset:10896
	s_waitcnt lgkmcnt(12)
	v_fma_f32 v184, -v72, v183, v184
	v_fma_f32 v185, v72, v182, v185
	v_fma_f32 v184, v74, v182, v184
	v_fma_f32 v185, v74, v183, v185
	v_cvt_pk_bf16_f32 v197, v184, v185
	ds_write_b32 v97, v197 offset:11168
	s_waitcnt lgkmcnt(11)
	v_fma_f32 v186, -v72, v185, v186
	v_fma_f32 v187, v72, v184, v187
	v_fma_f32 v186, v74, v184, v186
	v_fma_f32 v187, v74, v185, v187
	v_cvt_pk_bf16_f32 v198, v186, v187
	ds_write_b32 v97, v198 offset:11440
	s_waitcnt lgkmcnt(10)
	v_fma_f32 v188, -v72, v187, v188
	v_fma_f32 v189, v72, v186, v189
	v_fma_f32 v188, v74, v186, v188
	v_fma_f32 v189, v74, v187, v189
	v_cvt_pk_bf16_f32 v197, v188, v189
	ds_write_b32 v97, v197 offset:11712
	s_waitcnt lgkmcnt(9)
	v_fma_f32 v190, -v72, v189, v190
	v_fma_f32 v191, v72, v188, v191
	v_fma_f32 v190, v74, v188, v190
	v_fma_f32 v191, v74, v189, v191
	v_cvt_pk_bf16_f32 v198, v190, v191
	ds_write_b32 v97, v198 offset:11984
	s_waitcnt lgkmcnt(8)
	v_fma_f32 v192, -v72, v191, v192
	v_fma_f32 v193, v72, v190, v193
	v_fma_f32 v192, v74, v190, v192
	v_fma_f32 v193, v74, v191, v193
	v_cvt_pk_bf16_f32 v197, v192, v193
	ds_write_b32 v97, v197 offset:12256
	s_waitcnt lgkmcnt(7)
	v_fma_f32 v194, -v72, v193, v194
	v_fma_f32 v195, v72, v192, v195
	v_fma_f32 v194, v74, v192, v194
	v_fma_f32 v195, v74, v193, v195
	v_cvt_pk_bf16_f32 v198, v194, v195
	ds_write_b32 v97, v198 offset:12528
	s_branch .Ls5ct2_join

.Ls5ct2_join:
	v_mov_b32_e32 v120, v194
	v_mov_b32_e32 v121, v195
	s_waitcnt lgkmcnt(0)
	v_add_u32_e32 v196, v99, v93
	ds_read_b128 v[132:135], v196 offset:8448
	ds_read_b128 v[136:139], v196 offset:8512
	ds_read_b128 v[140:143], v196 offset:8576
	ds_read_b128 v[144:147], v196 offset:8640
	s_not_b32 s14, s3
	s_add_i32 s18, s2, s14
	s_and_b64 s[14:15], s[0:1], exec
	s_cselect_b32 s14, s3, s18
	s_add_i32 s3, s3, 1
	s_waitcnt lgkmcnt(3)
	v_mfma_f32_16x16x32_bf16 v[202:205], v[48:51], v[132:135], 0
	s_waitcnt lgkmcnt(2)
	v_mfma_f32_16x16x32_bf16 v[202:205], v[52:55], v[136:139], v[202:205]
	s_waitcnt lgkmcnt(1)
	v_mfma_f32_16x16x32_bf16 v[202:205], v[56:59], v[140:143], v[202:205]
	s_waitcnt lgkmcnt(0)
	v_mfma_f32_16x16x32_bf16 v[202:205], v[60:63], v[144:147], v[202:205]
	v_lshl_add_u32 v200, s14, 4, v103
	v_ashrrev_i32_e32 v201, 31, v200
	v_lshlrev_b64 v[200:201], 12, v[200:201]
	v_lshl_add_u64 v[200:201], v[78:79], 0, v[200:201]
	s_nop 3
	v_cvt_pk_bf16_f32 v202, v202, v203
	v_cvt_pk_bf16_f32 v203, v204, v205
	global_store_dwordx2 v[200:201], v[202:203], off
	s_waitcnt vmcnt(4)
	v_mfma_f32_16x16x32_bf16 v[132:135], v[4:7], v[44:47], 0
	v_mfma_f32_16x16x32_bf16 v[136:139], v[8:11], v[44:47], 0
	v_mfma_f32_16x16x32_bf16 v[140:143], v[12:15], v[44:47], 0
	v_mfma_f32_16x16x32_bf16 v[144:147], v[16:19], v[44:47], 0
	v_mfma_f32_16x16x32_bf16 v[148:151], v[20:23], v[44:47], 0
	v_mfma_f32_16x16x32_bf16 v[152:155], v[24:27], v[44:47], 0
	v_mfma_f32_16x16x32_bf16 v[156:159], v[28:31], v[44:47], 0
	v_mfma_f32_16x16x32_bf16 v[160:163], v[32:35], v[44:47], 0
	v_add_u32_e32 v196, v89, v93
	ds_write_b128 v196, v[132:135]
	ds_write_b128 v196, v[136:139] offset:64
	ds_write_b128 v196, v[140:143] offset:128
	ds_write_b128 v196, v[144:147] offset:192
	ds_write_b128 v196, v[148:151] offset:256
	ds_write_b128 v196, v[152:155] offset:320
	ds_write_b128 v196, v[156:159] offset:384
	ds_write_b128 v196, v[160:163] offset:448
	s_waitcnt lgkmcnt(0)
	s_and_b64 s[14:15], s[0:1], exec
	s_cbranch_scc0 .Ls5ct3_bwd
	ds_read_b64 v[164:165], v95
	ds_read_b64 v[166:167], v95 offset:528
	ds_read_b64 v[168:169], v95 offset:1056
	ds_read_b64 v[170:171], v95 offset:1584
	ds_read_b64 v[172:173], v95 offset:2112
	ds_read_b64 v[174:175], v95 offset:2640
	ds_read_b64 v[176:177], v95 offset:3168
	ds_read_b64 v[178:179], v95 offset:3696
	s_waitcnt lgkmcnt(7)
	v_fma_f32 v164, -v72, v121, v164
	v_fma_f32 v165, v72, v120, v165
	v_fma_f32 v164, v74, v120, v164
	v_fma_f32 v165, v74, v121, v165
	v_cvt_pk_bf16_f32 v197, v164, v165
	ds_write_b32 v97, v197 offset:8448
	ds_read_b64 v[180:181], v95 offset:4224
	s_waitcnt lgkmcnt(8)
	v_fma_f32 v166, -v72, v165, v166
	v_fma_f32 v167, v72, v164, v167
	v_fma_f32 v166, v74, v164, v166
	v_fma_f32 v167, v74, v165, v167
	v_cvt_pk_bf16_f32 v198, v166, v167
	ds_write_b32 v97, v198 offset:8720
	ds_read_b64 v[182:183], v95 offset:4752
	s_waitcnt lgkmcnt(9)
	v_fma_f32 v168, -v72, v167, v168
	v_fma_f32 v169, v72, v166, v169
	v_fma_f32 v168, v74, v166, v168
	v_fma_f32 v169, v74, v167, v169
	v_cvt_pk_bf16_f32 v197, v168, v169
	ds_write_b32 v97, v197 offset:8992
	ds_read_b64 v[184:185], v95 offset:5280
	s_waitcnt lgkmcnt(10)
	v_fma_f32 v170, -v72, v169, v170
	v_fma_f32 v171, v72, v168, v171
	v_fma_f32 v170, v74, v168, v170
	v_fma_f32 v171, v74, v169, v171
	v_cvt_pk_bf16_f32 v198, v170, v171
	ds_write_b32 v97, v198 offset:9264
	ds_read_b64 v[186:187], v95 offset:5808
	s_waitcnt lgkmcnt(11)
	v_fma_f32 v172, -v72, v171, v172
	v_fma_f32 v173, v72, v170, v173
	v_fma_f32 v172, v74, v170, v172
	v_fma_f32 v173, v74, v171, v173
	v_cvt_pk_bf16_f32 v197, v172, v173
	ds_write_b32 v97, v197 offset:9536
	ds_read_b64 v[188:189], v95 offset:6336
	s_waitcnt lgkmcnt(12)
	v_fma_f32 v174, -v72, v173, v174
	v_fma_f32 v175, v72, v172, v175
	v_fma_f32 v174, v74, v172, v174
	v_fma_f32 v175, v74, v173, v175
	v_cvt_pk_bf16_f32 v198, v174, v175
	ds_write_b32 v97, v198 offset:9808
	ds_read_b64 v[190:191], v95 offset:6864
	s_waitcnt lgkmcnt(13)
	v_fma_f32 v176, -v72, v175, v176
	v_fma_f32 v177, v72, v174, v177
	v_fma_f32 v176, v74, v174, v176
	v_fma_f32 v177, v74, v175, v177
	v_cvt_pk_bf16_f32 v197, v176, v177
	ds_write_b32 v97, v197 offset:10080
	ds_read_b64 v[192:193], v95 offset:7392
	s_waitcnt lgkmcnt(14)
	v_fma_f32 v178, -v72, v177, v178
	v_fma_f32 v179, v72, v176, v179
	v_fma_f32 v178, v74, v176, v178
	v_fma_f32 v179, v74, v177, v179
	v_cvt_pk_bf16_f32 v198, v178, v179
	ds_write_b32 v97, v198 offset:10352
	ds_read_b64 v[194:195], v95 offset:7920
	s_waitcnt lgkmcnt(14)
	v_fma_f32 v180, -v72, v179, v180
	v_fma_f32 v181, v72, v178, v181
	v_fma_f32 v180, v74, v178, v180
	v_fma_f32 v181, v74, v179, v181
	v_cvt_pk_bf16_f32 v197, v180, v181
	ds_write_b32 v97, v197 offset:10624
	s_waitcnt lgkmcnt(13)
	v_fma_f32 v182, -v72, v181, v182
	v_fma_f32 v183, v72, v180, v183
	v_fma_f32 v182, v74, v180, v182
	v_fma_f32 v183, v74, v181, v183
	v_cvt_pk_bf16_f32 v198, v182, v183
	ds_write_b32 v97, v198 offset:10896
	s_waitcnt lgkmcnt(12)
	v_fma_f32 v184, -v72, v183, v184
	v_fma_f32 v185, v72, v182, v185
	v_fma_f32 v184, v74, v182, v184
	v_fma_f32 v185, v74, v183, v185
	v_cvt_pk_bf16_f32 v197, v184, v185
	ds_write_b32 v97, v197 offset:11168
	s_waitcnt lgkmcnt(11)
	v_fma_f32 v186, -v72, v185, v186
	v_fma_f32 v187, v72, v184, v187
	v_fma_f32 v186, v74, v184, v186
	v_fma_f32 v187, v74, v185, v187
	v_cvt_pk_bf16_f32 v198, v186, v187
	ds_write_b32 v97, v198 offset:11440
	s_waitcnt lgkmcnt(10)
	v_fma_f32 v188, -v72, v187, v188
	v_fma_f32 v189, v72, v186, v189
	v_fma_f32 v188, v74, v186, v188
	v_fma_f32 v189, v74, v187, v189
	v_cvt_pk_bf16_f32 v197, v188, v189
	ds_write_b32 v97, v197 offset:11712
	s_waitcnt lgkmcnt(9)
	v_fma_f32 v190, -v72, v189, v190
	v_fma_f32 v191, v72, v188, v191
	v_fma_f32 v190, v74, v188, v190
	v_fma_f32 v191, v74, v189, v191
	v_cvt_pk_bf16_f32 v198, v190, v191
	ds_write_b32 v97, v198 offset:11984
	s_waitcnt lgkmcnt(8)
	v_fma_f32 v192, -v72, v191, v192
	v_fma_f32 v193, v72, v190, v193
	v_fma_f32 v192, v74, v190, v192
	v_fma_f32 v193, v74, v191, v193
	v_cvt_pk_bf16_f32 v197, v192, v193
	ds_write_b32 v97, v197 offset:12256
	s_waitcnt lgkmcnt(7)
	v_fma_f32 v194, -v72, v193, v194
	v_fma_f32 v195, v72, v192, v195
	v_fma_f32 v194, v74, v192, v194
	v_fma_f32 v195, v74, v193, v195
	v_cvt_pk_bf16_f32 v198, v194, v195
	ds_write_b32 v97, v198 offset:12528
	s_branch .Ls5ct3_join

.Ls5ct3_join:
	v_mov_b32_e32 v120, v194
	v_mov_b32_e32 v121, v195
	s_waitcnt lgkmcnt(0)
	v_add_u32_e32 v196, v99, v93
	ds_read_b128 v[132:135], v196 offset:8448
	ds_read_b128 v[136:139], v196 offset:8512
	ds_read_b128 v[140:143], v196 offset:8576
	ds_read_b128 v[144:147], v196 offset:8640
	s_not_b32 s14, s3
	s_add_i32 s18, s2, s14
	s_and_b64 s[14:15], s[0:1], exec
	s_cselect_b32 s14, s3, s18
	s_add_i32 s3, s3, 1
	s_waitcnt lgkmcnt(3)
	v_mfma_f32_16x16x32_bf16 v[202:205], v[48:51], v[132:135], 0
	s_waitcnt lgkmcnt(2)
	v_mfma_f32_16x16x32_bf16 v[202:205], v[52:55], v[136:139], v[202:205]
	s_waitcnt lgkmcnt(1)
	v_mfma_f32_16x16x32_bf16 v[202:205], v[56:59], v[140:143], v[202:205]
	s_waitcnt lgkmcnt(0)
	v_mfma_f32_16x16x32_bf16 v[202:205], v[60:63], v[144:147], v[202:205]
	v_lshl_add_u32 v200, s14, 4, v103
	v_ashrrev_i32_e32 v201, 31, v200
	v_lshlrev_b64 v[200:201], 12, v[200:201]
	v_lshl_add_u64 v[200:201], v[78:79], 0, v[200:201]
	s_nop 3
	v_cvt_pk_bf16_f32 v202, v202, v203
	v_cvt_pk_bf16_f32 v203, v204, v205
	global_store_dwordx2 v[200:201], v[202:203], off
	s_branch .LBB0_848

.LBB0_908:
	s_or_b64 exec, exec, s[12:13]
	v_max_f32_e32 v105, v105, v105
	v_min_f32_e32 v105, 0xb8d1b717, v105
	v_mul_f32_e32 v103, v103, v105
	v_mul_f32_e32 v105, 0x3fb8aa3b, v103
	v_fma_f32 v125, v103, s27, -v105
	v_rndne_f32_e32 v126, v105
	v_fmac_f32_e32 v125, 0x32a5705f, v103
	v_sub_f32_e32 v105, v105, v126
	v_add_f32_e32 v105, v105, v125
	v_cvt_i32_f32_e32 v125, v126
	v_exp_f32_e32 v105, v105
	v_cmp_ngt_f32_e32 vcc, s29, v103
	v_xor_b32_e32 v122, v122, v107
	s_waitcnt vmcnt(0)
	v_cvt_pk_bf16_f32 v60, v60, -v64
	v_ldexp_f32 v105, v105, v125
	v_cndmask_b32_e32 v105, 0, v105, vcc
	v_cmp_nlt_f32_e32 vcc, s10, v103
	v_cmp_class_f32_e64 s[46:47], v107, s28
	v_cvt_pk_bf16_f32 v56, v56, -v72
	v_cndmask_b32_e32 v103, v223, v105, vcc
	v_mul_f32_e32 v105, v123, v123
	v_fmamk_f32 v125, v105, 0xb94c1982, v219
	v_fmaak_f32 v125, v105, v125, 0xbe2aaa9d
	v_mul_f32_e32 v125, v105, v125
	v_fmac_f32_e32 v123, v123, v125
	v_fmamk_f32 v125, v105, 0x37d75334, v220
	v_fmaak_f32 v125, v105, v125, 0x3d2aabf7
	v_fmaak_f32 v125, v105, v125, 0xbf000004
	v_fma_f32 v105, v105, v125, 1.0
	v_lshlrev_b32_e32 v125, 30, v124
	v_and_b32_e32 v124, 1, v124
	v_cmp_eq_u32_e32 vcc, 0, v124
	v_xor_b32_e32 v64, 0x80000000, v123
	v_and_b32_e32 v126, 0x80000000, v125
	v_cndmask_b32_e32 v124, v105, v123, vcc
	v_xor_b32_e32 v122, v122, v124
	v_cndmask_b32_e32 v64, v64, v105, vcc
	v_xor_b32_e32 v122, v122, v126
	v_bitop3_b32 v64, v64, v125, s33 bitop3:0x78
	v_cndmask_b32_e64 v107, v251, v122, s[46:47]
	v_cndmask_b32_e64 v64, v251, v64, s[46:47]
	v_cvt_pk_bf16_f32 v58, v58, -v74
	v_mul_f32_e32 v72, v103, v107
	v_mul_f32_e32 v74, v103, v64
	s_lshl_b32 s62, s15, 1
	s_mov_b32 s4, 0
	v_cvt_pk_bf16_f32 v48, v48, -v80
	v_cvt_pk_bf16_f32 v49, v49, -v81
	v_cvt_pk_bf16_f32 v50, v50, -v82
	v_cvt_pk_bf16_f32 v51, v51, -v83
	v_cvt_pk_bf16_f32 v52, v52, -v76
	v_cvt_pk_bf16_f32 v53, v53, -v77
	v_cvt_pk_bf16_f32 v54, v54, -v78
	v_cvt_pk_bf16_f32 v55, v55, -v79
	v_cvt_pk_bf16_f32 v57, v57, -v73
	v_cvt_pk_bf16_f32 v59, v59, -v75
	v_cvt_pk_bf16_f32 v61, v61, -v65
	v_cvt_pk_bf16_f32 v62, v62, -v66
	v_cvt_pk_bf16_f32 v63, v63, -v67
	s_add_i32 s14, s3, -5
	v_lshl_add_u64 v[76:77], v[90:91], 0, s[62:63]
	v_lshl_add_u64 v[78:79], v[110:111], 0, s[62:63]
	v_mov_b32_e32 v75, v74
	v_mov_b32_e32 v73, v72
	s_add_i32 s15, s3, -5
	s_mov_b32 s98, 0x10000
	s_and_b64 s[12:13], s[54:55], exec
	s_cselect_b32 s15, 4, s15
	s_cselect_b32 s99, 0, -1
	s_cselect_b32 s98, s98, 0xffff0000
	v_lshl_add_u32 v64, s15, 4, v2
	v_ashrrev_i32_e32 v65, 31, v64
	v_lshlrev_b64 v[64:65], 12, v[64:65]
	v_lshl_add_u64 v[64:65], v[76:77], 0, v[64:65]
.Ls5l_main:
	s_waitcnt vmcnt(7)
	v_mfma_f32_16x16x32_bf16 v[132:135], v[4:7], v[68:71], 0
	v_mfma_f32_16x16x32_bf16 v[136:139], v[8:11], v[68:71], 0
	v_mfma_f32_16x16x32_bf16 v[140:143], v[12:15], v[68:71], 0
	v_mfma_f32_16x16x32_bf16 v[144:147], v[16:19], v[68:71], 0
	v_mfma_f32_16x16x32_bf16 v[148:151], v[20:23], v[68:71], 0
	v_mfma_f32_16x16x32_bf16 v[152:155], v[24:27], v[68:71], 0
	v_mfma_f32_16x16x32_bf16 v[156:159], v[28:31], v[68:71], 0
	v_mfma_f32_16x16x32_bf16 v[160:163], v[32:35], v[68:71], 0
	s_and_saveexec_b64 s[18:19], s[40:41]
	global_load_dwordx4 v[68:71], v[64:65], off
	s_mov_b64 exec, s[18:19]
	v_lshl_add_u64 v[64:65], v[64:65], 0, s[98:99]
	v_add_u32_e32 v196, v89, v93
	ds_write_b128 v196, v[132:135]
	ds_write_b128 v196, v[136:139] offset:64
	ds_write_b128 v196, v[140:143] offset:128
	ds_write_b128 v196, v[144:147] offset:192
	ds_write_b128 v196, v[148:151] offset:256
	ds_write_b128 v196, v[152:155] offset:320
	ds_write_b128 v196, v[156:159] offset:384
	ds_write_b128 v196, v[160:163] offset:448
	s_waitcnt lgkmcnt(0)
	s_and_b64 s[12:13], s[54:55], exec
	s_cbranch_scc0 .Ls5lm0_bwd
	ds_read_b64 v[164:165], v95
	ds_read_b64 v[166:167], v95 offset:528
	ds_read_b64 v[168:169], v95 offset:1056
	ds_read_b64 v[170:171], v95 offset:1584
	ds_read_b64 v[172:173], v95 offset:2112
	ds_read_b64 v[174:175], v95 offset:2640
	ds_read_b64 v[176:177], v95 offset:3168
	ds_read_b64 v[178:179], v95 offset:3696
	s_waitcnt lgkmcnt(7)
	v_fma_f32 v164, -v72, v121, v164
	v_fma_f32 v165, v72, v120, v165
	v_fma_f32 v164, v74, v120, v164
	v_fma_f32 v165, v74, v121, v165
	v_cvt_pk_bf16_f32 v197, v164, v165
	ds_write_b32 v97, v197 offset:8448
	ds_read_b64 v[180:181], v95 offset:4224
	s_waitcnt lgkmcnt(8)
	v_fma_f32 v166, -v72, v165, v166
	v_fma_f32 v167, v72, v164, v167
	v_fma_f32 v166, v74, v164, v166
	v_fma_f32 v167, v74, v165, v167
	v_cvt_pk_bf16_f32 v198, v166, v167
	ds_write_b32 v97, v198 offset:8720
	ds_read_b64 v[182:183], v95 offset:4752
	s_waitcnt lgkmcnt(9)
	v_fma_f32 v168, -v72, v167, v168
	v_fma_f32 v169, v72, v166, v169
	v_fma_f32 v168, v74, v166, v168
	v_fma_f32 v169, v74, v167, v169
	v_cvt_pk_bf16_f32 v197, v168, v169
	ds_write_b32 v97, v197 offset:8992
	ds_read_b64 v[184:185], v95 offset:5280
	s_waitcnt lgkmcnt(10)
	v_fma_f32 v170, -v72, v169, v170
	v_fma_f32 v171, v72, v168, v171
	v_fma_f32 v170, v74, v168, v170
	v_fma_f32 v171, v74, v169, v171
	v_cvt_pk_bf16_f32 v198, v170, v171
	ds_write_b32 v97, v198 offset:9264
	ds_read_b64 v[186:187], v95 offset:5808
	s_waitcnt lgkmcnt(11)
	v_fma_f32 v172, -v72, v171, v172
	v_fma_f32 v173, v72, v170, v173
	v_fma_f32 v172, v74, v170, v172
	v_fma_f32 v173, v74, v171, v173
	v_cvt_pk_bf16_f32 v197, v172, v173
	ds_write_b32 v97, v197 offset:9536
	ds_read_b64 v[188:189], v95 offset:6336
	s_waitcnt lgkmcnt(12)
	v_fma_f32 v174, -v72, v173, v174
	v_fma_f32 v175, v72, v172, v175
	v_fma_f32 v174, v74, v172, v174
	v_fma_f32 v175, v74, v173, v175
	v_cvt_pk_bf16_f32 v198, v174, v175
	ds_write_b32 v97, v198 offset:9808
	ds_read_b64 v[190:191], v95 offset:6864
	s_waitcnt lgkmcnt(13)
	v_fma_f32 v176, -v72, v175, v176
	v_fma_f32 v177, v72, v174, v177
	v_fma_f32 v176, v74, v174, v176
	v_fma_f32 v177, v74, v175, v177
	v_cvt_pk_bf16_f32 v197, v176, v177
	ds_write_b32 v97, v197 offset:10080
	ds_read_b64 v[192:193], v95 offset:7392
	s_waitcnt lgkmcnt(14)
	v_fma_f32 v178, -v72, v177, v178
	v_fma_f32 v179, v72, v176, v179
	v_fma_f32 v178, v74, v176, v178
	v_fma_f32 v179, v74, v177, v179
	v_cvt_pk_bf16_f32 v198, v178, v179
	ds_write_b32 v97, v198 offset:10352
	ds_read_b64 v[194:195], v95 offset:7920
	s_waitcnt lgkmcnt(14)
	v_fma_f32 v180, -v72, v179, v180
	v_fma_f32 v181, v72, v178, v181
	v_fma_f32 v180, v74, v178, v180
	v_fma_f32 v181, v74, v179, v181
	v_cvt_pk_bf16_f32 v197, v180, v181
	ds_write_b32 v97, v197 offset:10624
	s_waitcnt lgkmcnt(13)
	v_fma_f32 v182, -v72, v181, v182
	v_fma_f32 v183, v72, v180, v183
	v_fma_f32 v182, v74, v180, v182
	v_fma_f32 v183, v74, v181, v183
	v_cvt_pk_bf16_f32 v198, v182, v183
	ds_write_b32 v97, v198 offset:10896
	s_waitcnt lgkmcnt(12)
	v_fma_f32 v184, -v72, v183, v184
	v_fma_f32 v185, v72, v182, v185
	v_fma_f32 v184, v74, v182, v184
	v_fma_f32 v185, v74, v183, v185
	v_cvt_pk_bf16_f32 v197, v184, v185
	ds_write_b32 v97, v197 offset:11168
	s_waitcnt lgkmcnt(11)
	v_fma_f32 v186, -v72, v185, v186
	v_fma_f32 v187, v72, v184, v187
	v_fma_f32 v186, v74, v184, v186
	v_fma_f32 v187, v74, v185, v187
	v_cvt_pk_bf16_f32 v198, v186, v187
	ds_write_b32 v97, v198 offset:11440
	s_waitcnt lgkmcnt(10)
	v_fma_f32 v188, -v72, v187, v188
	v_fma_f32 v189, v72, v186, v189
	v_fma_f32 v188, v74, v186, v188
	v_fma_f32 v189, v74, v187, v189
	v_cvt_pk_bf16_f32 v197, v188, v189
	ds_write_b32 v97, v197 offset:11712
	s_waitcnt lgkmcnt(9)
	v_fma_f32 v190, -v72, v189, v190
	v_fma_f32 v191, v72, v188, v191
	v_fma_f32 v190, v74, v188, v190
	v_fma_f32 v191, v74, v189, v191
	v_cvt_pk_bf16_f32 v198, v190, v191
	ds_write_b32 v97, v198 offset:11984
	s_waitcnt lgkmcnt(8)
	v_fma_f32 v192, -v72, v191, v192
	v_fma_f32 v193, v72, v190, v193
	v_fma_f32 v192, v74, v190, v192
	v_fma_f32 v193, v74, v191, v193
	v_cvt_pk_bf16_f32 v197, v192, v193
	ds_write_b32 v97, v197 offset:12256
	s_waitcnt lgkmcnt(7)
	v_fma_f32 v194, -v72, v193, v194
	v_fma_f32 v195, v72, v192, v195
	v_fma_f32 v194, v74, v192, v194
	v_fma_f32 v195, v74, v193, v195
	v_cvt_pk_bf16_f32 v198, v194, v195
	ds_write_b32 v97, v198 offset:12528
	s_branch .Ls5lm0_join

.Ls5lm0_join:
	v_mov_b32_e32 v120, v194
	v_mov_b32_e32 v121, v195
	s_waitcnt lgkmcnt(0)
	v_add_u32_e32 v196, v99, v93
	ds_read_b128 v[132:135], v196 offset:8448
	ds_read_b128 v[136:139], v196 offset:8512
	ds_read_b128 v[140:143], v196 offset:8576
	ds_read_b128 v[144:147], v196 offset:8640
	s_not_b32 s12, s4
	s_add_i32 s15, s3, s12
	s_and_b64 s[12:13], s[54:55], exec
	s_cselect_b32 s12, s4, s15
	s_add_i32 s4, s4, 1
	s_waitcnt lgkmcnt(3)
	v_mfma_f32_16x16x32_bf16 v[202:205], v[48:51], v[132:135], 0
	s_waitcnt lgkmcnt(2)
	v_mfma_f32_16x16x32_bf16 v[202:205], v[52:55], v[136:139], v[202:205]
	s_waitcnt lgkmcnt(1)
	v_mfma_f32_16x16x32_bf16 v[202:205], v[56:59], v[140:143], v[202:205]
	s_waitcnt lgkmcnt(0)
	v_mfma_f32_16x16x32_bf16 v[202:205], v[60:63], v[144:147], v[202:205]
	v_lshl_add_u32 v200, s12, 4, v2
	v_ashrrev_i32_e32 v201, 31, v200
	v_lshlrev_b64 v[200:201], 12, v[200:201]
	v_lshl_add_u64 v[200:201], v[78:79], 0, v[200:201]
	s_nop 3
	v_cvt_pk_bf16_f32 v202, v202, v203
	v_cvt_pk_bf16_f32 v203, v204, v205
	global_store_dwordx2 v[200:201], v[202:203], off
	s_waitcnt vmcnt(7)
	v_mfma_f32_16x16x32_bf16 v[132:135], v[4:7], v[36:39], 0
	v_mfma_f32_16x16x32_bf16 v[136:139], v[8:11], v[36:39], 0
	v_mfma_f32_16x16x32_bf16 v[140:143], v[12:15], v[36:39], 0
	v_mfma_f32_16x16x32_bf16 v[144:147], v[16:19], v[36:39], 0
	v_mfma_f32_16x16x32_bf16 v[148:151], v[20:23], v[36:39], 0
	v_mfma_f32_16x16x32_bf16 v[152:155], v[24:27], v[36:39], 0
	v_mfma_f32_16x16x32_bf16 v[156:159], v[28:31], v[36:39], 0
	v_mfma_f32_16x16x32_bf16 v[160:163], v[32:35], v[36:39], 0
	s_and_saveexec_b64 s[18:19], s[40:41]
	global_load_dwordx4 v[36:39], v[64:65], off
	s_mov_b64 exec, s[18:19]
	v_lshl_add_u64 v[64:65], v[64:65], 0, s[98:99]
	v_add_u32_e32 v196, v89, v93
	ds_write_b128 v196, v[132:135]
	ds_write_b128 v196, v[136:139] offset:64
	ds_write_b128 v196, v[140:143] offset:128
	ds_write_b128 v196, v[144:147] offset:192
	ds_write_b128 v196, v[148:151] offset:256
	ds_write_b128 v196, v[152:155] offset:320
	ds_write_b128 v196, v[156:159] offset:384
	ds_write_b128 v196, v[160:163] offset:448
	s_waitcnt lgkmcnt(0)
	s_and_b64 s[12:13], s[54:55], exec
	s_cbranch_scc0 .Ls5lm1_bwd
	ds_read_b64 v[164:165], v95
	ds_read_b64 v[166:167], v95 offset:528
	ds_read_b64 v[168:169], v95 offset:1056
	ds_read_b64 v[170:171], v95 offset:1584
	ds_read_b64 v[172:173], v95 offset:2112
	ds_read_b64 v[174:175], v95 offset:2640
	ds_read_b64 v[176:177], v95 offset:3168
	ds_read_b64 v[178:179], v95 offset:3696
	s_waitcnt lgkmcnt(7)
	v_fma_f32 v164, -v72, v121, v164
	v_fma_f32 v165, v72, v120, v165
	v_fma_f32 v164, v74, v120, v164
	v_fma_f32 v165, v74, v121, v165
	v_cvt_pk_bf16_f32 v197, v164, v165
	ds_write_b32 v97, v197 offset:8448
	ds_read_b64 v[180:181], v95 offset:4224
	s_waitcnt lgkmcnt(8)
	v_fma_f32 v166, -v72, v165, v166
	v_fma_f32 v167, v72, v164, v167
	v_fma_f32 v166, v74, v164, v166
	v_fma_f32 v167, v74, v165, v167
	v_cvt_pk_bf16_f32 v198, v166, v167
	ds_write_b32 v97, v198 offset:8720
	ds_read_b64 v[182:183], v95 offset:4752
	s_waitcnt lgkmcnt(9)
	v_fma_f32 v168, -v72, v167, v168
	v_fma_f32 v169, v72, v166, v169
	v_fma_f32 v168, v74, v166, v168
	v_fma_f32 v169, v74, v167, v169
	v_cvt_pk_bf16_f32 v197, v168, v169
	ds_write_b32 v97, v197 offset:8992
	ds_read_b64 v[184:185], v95 offset:5280
	s_waitcnt lgkmcnt(10)
	v_fma_f32 v170, -v72, v169, v170
	v_fma_f32 v171, v72, v168, v171
	v_fma_f32 v170, v74, v168, v170
	v_fma_f32 v171, v74, v169, v171
	v_cvt_pk_bf16_f32 v198, v170, v171
	ds_write_b32 v97, v198 offset:9264
	ds_read_b64 v[186:187], v95 offset:5808
	s_waitcnt lgkmcnt(11)
	v_fma_f32 v172, -v72, v171, v172
	v_fma_f32 v173, v72, v170, v173
	v_fma_f32 v172, v74, v170, v172
	v_fma_f32 v173, v74, v171, v173
	v_cvt_pk_bf16_f32 v197, v172, v173
	ds_write_b32 v97, v197 offset:9536
	ds_read_b64 v[188:189], v95 offset:6336
	s_waitcnt lgkmcnt(12)
	v_fma_f32 v174, -v72, v173, v174
	v_fma_f32 v175, v72, v172, v175
	v_fma_f32 v174, v74, v172, v174
	v_fma_f32 v175, v74, v173, v175
	v_cvt_pk_bf16_f32 v198, v174, v175
	ds_write_b32 v97, v198 offset:9808
	ds_read_b64 v[190:191], v95 offset:6864
	s_waitcnt lgkmcnt(13)
	v_fma_f32 v176, -v72, v175, v176
	v_fma_f32 v177, v72, v174, v177
	v_fma_f32 v176, v74, v174, v176
	v_fma_f32 v177, v74, v175, v177
	v_cvt_pk_bf16_f32 v197, v176, v177
	ds_write_b32 v97, v197 offset:10080
	ds_read_b64 v[192:193], v95 offset:7392
	s_waitcnt lgkmcnt(14)
	v_fma_f32 v178, -v72, v177, v178
	v_fma_f32 v179, v72, v176, v179
	v_fma_f32 v178, v74, v176, v178
	v_fma_f32 v179, v74, v177, v179
	v_cvt_pk_bf16_f32 v198, v178, v179
	ds_write_b32 v97, v198 offset:10352
	ds_read_b64 v[194:195], v95 offset:7920
	s_waitcnt lgkmcnt(14)
	v_fma_f32 v180, -v72, v179, v180
	v_fma_f32 v181, v72, v178, v181
	v_fma_f32 v180, v74, v178, v180
	v_fma_f32 v181, v74, v179, v181
	v_cvt_pk_bf16_f32 v197, v180, v181
	ds_write_b32 v97, v197 offset:10624
	s_waitcnt lgkmcnt(13)
	v_fma_f32 v182, -v72, v181, v182
	v_fma_f32 v183, v72, v180, v183
	v_fma_f32 v182, v74, v180, v182
	v_fma_f32 v183, v74, v181, v183
	v_cvt_pk_bf16_f32 v198, v182, v183
	ds_write_b32 v97, v198 offset:10896
	s_waitcnt lgkmcnt(12)
	v_fma_f32 v184, -v72, v183, v184
	v_fma_f32 v185, v72, v182, v185
	v_fma_f32 v184, v74, v182, v184
	v_fma_f32 v185, v74, v183, v185
	v_cvt_pk_bf16_f32 v197, v184, v185
	ds_write_b32 v97, v197 offset:11168
	s_waitcnt lgkmcnt(11)
	v_fma_f32 v186, -v72, v185, v186
	v_fma_f32 v187, v72, v184, v187
	v_fma_f32 v186, v74, v184, v186
	v_fma_f32 v187, v74, v185, v187
	v_cvt_pk_bf16_f32 v198, v186, v187
	ds_write_b32 v97, v198 offset:11440
	s_waitcnt lgkmcnt(10)
	v_fma_f32 v188, -v72, v187, v188
	v_fma_f32 v189, v72, v186, v189
	v_fma_f32 v188, v74, v186, v188
	v_fma_f32 v189, v74, v187, v189
	v_cvt_pk_bf16_f32 v197, v188, v189
	ds_write_b32 v97, v197 offset:11712
	s_waitcnt lgkmcnt(9)
	v_fma_f32 v190, -v72, v189, v190
	v_fma_f32 v191, v72, v188, v191
	v_fma_f32 v190, v74, v188, v190
	v_fma_f32 v191, v74, v189, v191
	v_cvt_pk_bf16_f32 v198, v190, v191
	ds_write_b32 v97, v198 offset:11984
	s_waitcnt lgkmcnt(8)
	v_fma_f32 v192, -v72, v191, v192
	v_fma_f32 v193, v72, v190, v193
	v_fma_f32 v192, v74, v190, v192
	v_fma_f32 v193, v74, v191, v193
	v_cvt_pk_bf16_f32 v197, v192, v193
	ds_write_b32 v97, v197 offset:12256
	s_waitcnt lgkmcnt(7)
	v_fma_f32 v194, -v72, v193, v194
	v_fma_f32 v195, v72, v192, v195
	v_fma_f32 v194, v74, v192, v194
	v_fma_f32 v195, v74, v193, v195
	v_cvt_pk_bf16_f32 v198, v194, v195
	ds_write_b32 v97, v198 offset:12528
	s_branch .Ls5lm1_join

.Ls5lm1_join:
	v_mov_b32_e32 v120, v194
	v_mov_b32_e32 v121, v195
	s_waitcnt lgkmcnt(0)
	v_add_u32_e32 v196, v99, v93
	ds_read_b128 v[132:135], v196 offset:8448
	ds_read_b128 v[136:139], v196 offset:8512
	ds_read_b128 v[140:143], v196 offset:8576
	ds_read_b128 v[144:147], v196 offset:8640
	s_not_b32 s12, s4
	s_add_i32 s15, s3, s12
	s_and_b64 s[12:13], s[54:55], exec
	s_cselect_b32 s12, s4, s15
	s_add_i32 s4, s4, 1
	s_waitcnt lgkmcnt(3)
	v_mfma_f32_16x16x32_bf16 v[202:205], v[48:51], v[132:135], 0
	s_waitcnt lgkmcnt(2)
	v_mfma_f32_16x16x32_bf16 v[202:205], v[52:55], v[136:139], v[202:205]
	s_waitcnt lgkmcnt(1)
	v_mfma_f32_16x16x32_bf16 v[202:205], v[56:59], v[140:143], v[202:205]
	s_waitcnt lgkmcnt(0)
	v_mfma_f32_16x16x32_bf16 v[202:205], v[60:63], v[144:147], v[202:205]
	v_lshl_add_u32 v200, s12, 4, v2
	v_ashrrev_i32_e32 v201, 31, v200
	v_lshlrev_b64 v[200:201], 12, v[200:201]
	v_lshl_add_u64 v[200:201], v[78:79], 0, v[200:201]
	s_nop 3
	v_cvt_pk_bf16_f32 v202, v202, v203
	v_cvt_pk_bf16_f32 v203, v204, v205
	global_store_dwordx2 v[200:201], v[202:203], off
	s_waitcnt vmcnt(7)
	v_mfma_f32_16x16x32_bf16 v[132:135], v[4:7], v[40:43], 0
	v_mfma_f32_16x16x32_bf16 v[136:139], v[8:11], v[40:43], 0
	v_mfma_f32_16x16x32_bf16 v[140:143], v[12:15], v[40:43], 0
	v_mfma_f32_16x16x32_bf16 v[144:147], v[16:19], v[40:43], 0
	v_mfma_f32_16x16x32_bf16 v[148:151], v[20:23], v[40:43], 0
	v_mfma_f32_16x16x32_bf16 v[152:155], v[24:27], v[40:43], 0
	v_mfma_f32_16x16x32_bf16 v[156:159], v[28:31], v[40:43], 0
	v_mfma_f32_16x16x32_bf16 v[160:163], v[32:35], v[40:43], 0
	s_and_saveexec_b64 s[18:19], s[40:41]
	global_load_dwordx4 v[40:43], v[64:65], off
	s_mov_b64 exec, s[18:19]
	v_lshl_add_u64 v[64:65], v[64:65], 0, s[98:99]
	v_add_u32_e32 v196, v89, v93
	ds_write_b128 v196, v[132:135]
	ds_write_b128 v196, v[136:139] offset:64
	ds_write_b128 v196, v[140:143] offset:128
	ds_write_b128 v196, v[144:147] offset:192
	ds_write_b128 v196, v[148:151] offset:256
	ds_write_b128 v196, v[152:155] offset:320
	ds_write_b128 v196, v[156:159] offset:384
	ds_write_b128 v196, v[160:163] offset:448
	s_waitcnt lgkmcnt(0)
	s_and_b64 s[12:13], s[54:55], exec
	s_cbranch_scc0 .Ls5lm2_bwd
	ds_read_b64 v[164:165], v95
	ds_read_b64 v[166:167], v95 offset:528
	ds_read_b64 v[168:169], v95 offset:1056
	ds_read_b64 v[170:171], v95 offset:1584
	ds_read_b64 v[172:173], v95 offset:2112
	ds_read_b64 v[174:175], v95 offset:2640
	ds_read_b64 v[176:177], v95 offset:3168
	ds_read_b64 v[178:179], v95 offset:3696
	s_waitcnt lgkmcnt(7)
	v_fma_f32 v164, -v72, v121, v164
	v_fma_f32 v165, v72, v120, v165
	v_fma_f32 v164, v74, v120, v164
	v_fma_f32 v165, v74, v121, v165
	v_cvt_pk_bf16_f32 v197, v164, v165
	ds_write_b32 v97, v197 offset:8448
	ds_read_b64 v[180:181], v95 offset:4224
	s_waitcnt lgkmcnt(8)
	v_fma_f32 v166, -v72, v165, v166
	v_fma_f32 v167, v72, v164, v167
	v_fma_f32 v166, v74, v164, v166
	v_fma_f32 v167, v74, v165, v167
	v_cvt_pk_bf16_f32 v198, v166, v167
	ds_write_b32 v97, v198 offset:8720
	ds_read_b64 v[182:183], v95 offset:4752
	s_waitcnt lgkmcnt(9)
	v_fma_f32 v168, -v72, v167, v168
	v_fma_f32 v169, v72, v166, v169
	v_fma_f32 v168, v74, v166, v168
	v_fma_f32 v169, v74, v167, v169
	v_cvt_pk_bf16_f32 v197, v168, v169
	ds_write_b32 v97, v197 offset:8992
	ds_read_b64 v[184:185], v95 offset:5280
	s_waitcnt lgkmcnt(10)
	v_fma_f32 v170, -v72, v169, v170
	v_fma_f32 v171, v72, v168, v171
	v_fma_f32 v170, v74, v168, v170
	v_fma_f32 v171, v74, v169, v171
	v_cvt_pk_bf16_f32 v198, v170, v171
	ds_write_b32 v97, v198 offset:9264
	ds_read_b64 v[186:187], v95 offset:5808
	s_waitcnt lgkmcnt(11)
	v_fma_f32 v172, -v72, v171, v172
	v_fma_f32 v173, v72, v170, v173
	v_fma_f32 v172, v74, v170, v172
	v_fma_f32 v173, v74, v171, v173
	v_cvt_pk_bf16_f32 v197, v172, v173
	ds_write_b32 v97, v197 offset:9536
	ds_read_b64 v[188:189], v95 offset:6336
	s_waitcnt lgkmcnt(12)
	v_fma_f32 v174, -v72, v173, v174
	v_fma_f32 v175, v72, v172, v175
	v_fma_f32 v174, v74, v172, v174
	v_fma_f32 v175, v74, v173, v175
	v_cvt_pk_bf16_f32 v198, v174, v175
	ds_write_b32 v97, v198 offset:9808
	ds_read_b64 v[190:191], v95 offset:6864
	s_waitcnt lgkmcnt(13)
	v_fma_f32 v176, -v72, v175, v176
	v_fma_f32 v177, v72, v174, v177
	v_fma_f32 v176, v74, v174, v176
	v_fma_f32 v177, v74, v175, v177
	v_cvt_pk_bf16_f32 v197, v176, v177
	ds_write_b32 v97, v197 offset:10080
	ds_read_b64 v[192:193], v95 offset:7392
	s_waitcnt lgkmcnt(14)
	v_fma_f32 v178, -v72, v177, v178
	v_fma_f32 v179, v72, v176, v179
	v_fma_f32 v178, v74, v176, v178
	v_fma_f32 v179, v74, v177, v179
	v_cvt_pk_bf16_f32 v198, v178, v179
	ds_write_b32 v97, v198 offset:10352
	ds_read_b64 v[194:195], v95 offset:7920
	s_waitcnt lgkmcnt(14)
	v_fma_f32 v180, -v72, v179, v180
	v_fma_f32 v181, v72, v178, v181
	v_fma_f32 v180, v74, v178, v180
	v_fma_f32 v181, v74, v179, v181
	v_cvt_pk_bf16_f32 v197, v180, v181
	ds_write_b32 v97, v197 offset:10624
	s_waitcnt lgkmcnt(13)
	v_fma_f32 v182, -v72, v181, v182
	v_fma_f32 v183, v72, v180, v183
	v_fma_f32 v182, v74, v180, v182
	v_fma_f32 v183, v74, v181, v183
	v_cvt_pk_bf16_f32 v198, v182, v183
	ds_write_b32 v97, v198 offset:10896
	s_waitcnt lgkmcnt(12)
	v_fma_f32 v184, -v72, v183, v184
	v_fma_f32 v185, v72, v182, v185
	v_fma_f32 v184, v74, v182, v184
	v_fma_f32 v185, v74, v183, v185
	v_cvt_pk_bf16_f32 v197, v184, v185
	ds_write_b32 v97, v197 offset:11168
	s_waitcnt lgkmcnt(11)
	v_fma_f32 v186, -v72, v185, v186
	v_fma_f32 v187, v72, v184, v187
	v_fma_f32 v186, v74, v184, v186
	v_fma_f32 v187, v74, v185, v187
	v_cvt_pk_bf16_f32 v198, v186, v187
	ds_write_b32 v97, v198 offset:11440
	s_waitcnt lgkmcnt(10)
	v_fma_f32 v188, -v72, v187, v188
	v_fma_f32 v189, v72, v186, v189
	v_fma_f32 v188, v74, v186, v188
	v_fma_f32 v189, v74, v187, v189
	v_cvt_pk_bf16_f32 v197, v188, v189
	ds_write_b32 v97, v197 offset:11712
	s_waitcnt lgkmcnt(9)
	v_fma_f32 v190, -v72, v189, v190
	v_fma_f32 v191, v72, v188, v191
	v_fma_f32 v190, v74, v188, v190
	v_fma_f32 v191, v74, v189, v191
	v_cvt_pk_bf16_f32 v198, v190, v191
	ds_write_b32 v97, v198 offset:11984
	s_waitcnt lgkmcnt(8)
	v_fma_f32 v192, -v72, v191, v192
	v_fma_f32 v193, v72, v190, v193
	v_fma_f32 v192, v74, v190, v192
	v_fma_f32 v193, v74, v191, v193
	v_cvt_pk_bf16_f32 v197, v192, v193
	ds_write_b32 v97, v197 offset:12256
	s_waitcnt lgkmcnt(7)
	v_fma_f32 v194, -v72, v193, v194
	v_fma_f32 v195, v72, v192, v195
	v_fma_f32 v194, v74, v192, v194
	v_fma_f32 v195, v74, v193, v195
	v_cvt_pk_bf16_f32 v198, v194, v195
	ds_write_b32 v97, v198 offset:12528
	s_branch .Ls5lm2_join

.Ls5lm2_join:
	v_mov_b32_e32 v120, v194
	v_mov_b32_e32 v121, v195
	s_waitcnt lgkmcnt(0)
	v_add_u32_e32 v196, v99, v93
	ds_read_b128 v[132:135], v196 offset:8448
	ds_read_b128 v[136:139], v196 offset:8512
	ds_read_b128 v[140:143], v196 offset:8576
	ds_read_b128 v[144:147], v196 offset:8640
	s_not_b32 s12, s4
	s_add_i32 s15, s3, s12
	s_and_b64 s[12:13], s[54:55], exec
	s_cselect_b32 s12, s4, s15
	s_add_i32 s4, s4, 1
	s_waitcnt lgkmcnt(3)
	v_mfma_f32_16x16x32_bf16 v[202:205], v[48:51], v[132:135], 0
	s_waitcnt lgkmcnt(2)
	v_mfma_f32_16x16x32_bf16 v[202:205], v[52:55], v[136:139], v[202:205]
	s_waitcnt lgkmcnt(1)
	v_mfma_f32_16x16x32_bf16 v[202:205], v[56:59], v[140:143], v[202:205]
	s_waitcnt lgkmcnt(0)
	v_mfma_f32_16x16x32_bf16 v[202:205], v[60:63], v[144:147], v[202:205]
	v_lshl_add_u32 v200, s12, 4, v2
	v_ashrrev_i32_e32 v201, 31, v200
	v_lshlrev_b64 v[200:201], 12, v[200:201]
	v_lshl_add_u64 v[200:201], v[78:79], 0, v[200:201]
	s_nop 3
	v_cvt_pk_bf16_f32 v202, v202, v203
	v_cvt_pk_bf16_f32 v203, v204, v205
	global_store_dwordx2 v[200:201], v[202:203], off
	s_waitcnt vmcnt(7)
	v_mfma_f32_16x16x32_bf16 v[132:135], v[4:7], v[44:47], 0
	v_mfma_f32_16x16x32_bf16 v[136:139], v[8:11], v[44:47], 0
	v_mfma_f32_16x16x32_bf16 v[140:143], v[12:15], v[44:47], 0
	v_mfma_f32_16x16x32_bf16 v[144:147], v[16:19], v[44:47], 0
	v_mfma_f32_16x16x32_bf16 v[148:151], v[20:23], v[44:47], 0
	v_mfma_f32_16x16x32_bf16 v[152:155], v[24:27], v[44:47], 0
	v_mfma_f32_16x16x32_bf16 v[156:159], v[28:31], v[44:47], 0
	v_mfma_f32_16x16x32_bf16 v[160:163], v[32:35], v[44:47], 0
	s_and_saveexec_b64 s[18:19], s[40:41]
	global_load_dwordx4 v[44:47], v[64:65], off
	s_mov_b64 exec, s[18:19]
	v_lshl_add_u64 v[64:65], v[64:65], 0, s[98:99]
	v_add_u32_e32 v196, v89, v93
	ds_write_b128 v196, v[132:135]
	ds_write_b128 v196, v[136:139] offset:64
	ds_write_b128 v196, v[140:143] offset:128
	ds_write_b128 v196, v[144:147] offset:192
	ds_write_b128 v196, v[148:151] offset:256
	ds_write_b128 v196, v[152:155] offset:320
	ds_write_b128 v196, v[156:159] offset:384
	ds_write_b128 v196, v[160:163] offset:448
	s_waitcnt lgkmcnt(0)
	s_and_b64 s[12:13], s[54:55], exec
	s_cbranch_scc0 .Ls5lm3_bwd
	ds_read_b64 v[164:165], v95
	ds_read_b64 v[166:167], v95 offset:528
	ds_read_b64 v[168:169], v95 offset:1056
	ds_read_b64 v[170:171], v95 offset:1584
	ds_read_b64 v[172:173], v95 offset:2112
	ds_read_b64 v[174:175], v95 offset:2640
	ds_read_b64 v[176:177], v95 offset:3168
	ds_read_b64 v[178:179], v95 offset:3696
	s_waitcnt lgkmcnt(7)
	v_fma_f32 v164, -v72, v121, v164
	v_fma_f32 v165, v72, v120, v165
	v_fma_f32 v164, v74, v120, v164
	v_fma_f32 v165, v74, v121, v165
	v_cvt_pk_bf16_f32 v197, v164, v165
	ds_write_b32 v97, v197 offset:8448
	ds_read_b64 v[180:181], v95 offset:4224
	s_waitcnt lgkmcnt(8)
	v_fma_f32 v166, -v72, v165, v166
	v_fma_f32 v167, v72, v164, v167
	v_fma_f32 v166, v74, v164, v166
	v_fma_f32 v167, v74, v165, v167
	v_cvt_pk_bf16_f32 v198, v166, v167
	ds_write_b32 v97, v198 offset:8720
	ds_read_b64 v[182:183], v95 offset:4752
	s_waitcnt lgkmcnt(9)
	v_fma_f32 v168, -v72, v167, v168
	v_fma_f32 v169, v72, v166, v169
	v_fma_f32 v168, v74, v166, v168
	v_fma_f32 v169, v74, v167, v169
	v_cvt_pk_bf16_f32 v197, v168, v169
	ds_write_b32 v97, v197 offset:8992
	ds_read_b64 v[184:185], v95 offset:5280
	s_waitcnt lgkmcnt(10)
	v_fma_f32 v170, -v72, v169, v170
	v_fma_f32 v171, v72, v168, v171
	v_fma_f32 v170, v74, v168, v170
	v_fma_f32 v171, v74, v169, v171
	v_cvt_pk_bf16_f32 v198, v170, v171
	ds_write_b32 v97, v198 offset:9264
	ds_read_b64 v[186:187], v95 offset:5808
	s_waitcnt lgkmcnt(11)
	v_fma_f32 v172, -v72, v171, v172
	v_fma_f32 v173, v72, v170, v173
	v_fma_f32 v172, v74, v170, v172
	v_fma_f32 v173, v74, v171, v173
	v_cvt_pk_bf16_f32 v197, v172, v173
	ds_write_b32 v97, v197 offset:9536
	ds_read_b64 v[188:189], v95 offset:6336
	s_waitcnt lgkmcnt(12)
	v_fma_f32 v174, -v72, v173, v174
	v_fma_f32 v175, v72, v172, v175
	v_fma_f32 v174, v74, v172, v174
	v_fma_f32 v175, v74, v173, v175
	v_cvt_pk_bf16_f32 v198, v174, v175
	ds_write_b32 v97, v198 offset:9808
	ds_read_b64 v[190:191], v95 offset:6864
	s_waitcnt lgkmcnt(13)
	v_fma_f32 v176, -v72, v175, v176
	v_fma_f32 v177, v72, v174, v177
	v_fma_f32 v176, v74, v174, v176
	v_fma_f32 v177, v74, v175, v177
	v_cvt_pk_bf16_f32 v197, v176, v177
	ds_write_b32 v97, v197 offset:10080
	ds_read_b64 v[192:193], v95 offset:7392
	s_waitcnt lgkmcnt(14)
	v_fma_f32 v178, -v72, v177, v178
	v_fma_f32 v179, v72, v176, v179
	v_fma_f32 v178, v74, v176, v178
	v_fma_f32 v179, v74, v177, v179
	v_cvt_pk_bf16_f32 v198, v178, v179
	ds_write_b32 v97, v198 offset:10352
	ds_read_b64 v[194:195], v95 offset:7920
	s_waitcnt lgkmcnt(14)
	v_fma_f32 v180, -v72, v179, v180
	v_fma_f32 v181, v72, v178, v181
	v_fma_f32 v180, v74, v178, v180
	v_fma_f32 v181, v74, v179, v181
	v_cvt_pk_bf16_f32 v197, v180, v181
	ds_write_b32 v97, v197 offset:10624
	s_waitcnt lgkmcnt(13)
	v_fma_f32 v182, -v72, v181, v182
	v_fma_f32 v183, v72, v180, v183
	v_fma_f32 v182, v74, v180, v182
	v_fma_f32 v183, v74, v181, v183
	v_cvt_pk_bf16_f32 v198, v182, v183
	ds_write_b32 v97, v198 offset:10896
	s_waitcnt lgkmcnt(12)
	v_fma_f32 v184, -v72, v183, v184
	v_fma_f32 v185, v72, v182, v185
	v_fma_f32 v184, v74, v182, v184
	v_fma_f32 v185, v74, v183, v185
	v_cvt_pk_bf16_f32 v197, v184, v185
	ds_write_b32 v97, v197 offset:11168
	s_waitcnt lgkmcnt(11)
	v_fma_f32 v186, -v72, v185, v186
	v_fma_f32 v187, v72, v184, v187
	v_fma_f32 v186, v74, v184, v186
	v_fma_f32 v187, v74, v185, v187
	v_cvt_pk_bf16_f32 v198, v186, v187
	ds_write_b32 v97, v198 offset:11440
	s_waitcnt lgkmcnt(10)
	v_fma_f32 v188, -v72, v187, v188
	v_fma_f32 v189, v72, v186, v189
	v_fma_f32 v188, v74, v186, v188
	v_fma_f32 v189, v74, v187, v189
	v_cvt_pk_bf16_f32 v197, v188, v189
	ds_write_b32 v97, v197 offset:11712
	s_waitcnt lgkmcnt(9)
	v_fma_f32 v190, -v72, v189, v190
	v_fma_f32 v191, v72, v188, v191
	v_fma_f32 v190, v74, v188, v190
	v_fma_f32 v191, v74, v189, v191
	v_cvt_pk_bf16_f32 v198, v190, v191
	ds_write_b32 v97, v198 offset:11984
	s_waitcnt lgkmcnt(8)
	v_fma_f32 v192, -v72, v191, v192
	v_fma_f32 v193, v72, v190, v193
	v_fma_f32 v192, v74, v190, v192
	v_fma_f32 v193, v74, v191, v193
	v_cvt_pk_bf16_f32 v197, v192, v193
	ds_write_b32 v97, v197 offset:12256
	s_waitcnt lgkmcnt(7)
	v_fma_f32 v194, -v72, v193, v194
	v_fma_f32 v195, v72, v192, v195
	v_fma_f32 v194, v74, v192, v194
	v_fma_f32 v195, v74, v193, v195
	v_cvt_pk_bf16_f32 v198, v194, v195
	ds_write_b32 v97, v198 offset:12528
	s_branch .Ls5lm3_join

.Ls5lm3_join:
	v_mov_b32_e32 v120, v194
	v_mov_b32_e32 v121, v195
	s_waitcnt lgkmcnt(0)
	v_add_u32_e32 v196, v99, v93
	ds_read_b128 v[132:135], v196 offset:8448
	ds_read_b128 v[136:139], v196 offset:8512
	ds_read_b128 v[140:143], v196 offset:8576
	ds_read_b128 v[144:147], v196 offset:8640
	s_not_b32 s12, s4
	s_add_i32 s15, s3, s12
	s_and_b64 s[12:13], s[54:55], exec
	s_cselect_b32 s12, s4, s15
	s_add_i32 s4, s4, 1
	s_waitcnt lgkmcnt(3)
	v_mfma_f32_16x16x32_bf16 v[202:205], v[48:51], v[132:135], 0
	s_waitcnt lgkmcnt(2)
	v_mfma_f32_16x16x32_bf16 v[202:205], v[52:55], v[136:139], v[202:205]
	s_waitcnt lgkmcnt(1)
	v_mfma_f32_16x16x32_bf16 v[202:205], v[56:59], v[140:143], v[202:205]
	s_waitcnt lgkmcnt(0)
	v_mfma_f32_16x16x32_bf16 v[202:205], v[60:63], v[144:147], v[202:205]
	v_lshl_add_u32 v200, s12, 4, v2
	v_ashrrev_i32_e32 v201, 31, v200
	v_lshlrev_b64 v[200:201], 12, v[200:201]
	v_lshl_add_u64 v[200:201], v[78:79], 0, v[200:201]
	s_nop 3
	v_cvt_pk_bf16_f32 v202, v202, v203
	v_cvt_pk_bf16_f32 v203, v204, v205
	global_store_dwordx2 v[200:201], v[202:203], off
	s_add_i32 s15, s4, 4
	s_cmp_lt_u32 s15, s3
	s_cbranch_scc1 .Ls5l_main
	s_waitcnt vmcnt(7)
	v_mfma_f32_16x16x32_bf16 v[132:135], v[4:7], v[68:71], 0
	v_mfma_f32_16x16x32_bf16 v[136:139], v[8:11], v[68:71], 0
	v_mfma_f32_16x16x32_bf16 v[140:143], v[12:15], v[68:71], 0
	v_mfma_f32_16x16x32_bf16 v[144:147], v[16:19], v[68:71], 0
	v_mfma_f32_16x16x32_bf16 v[148:151], v[20:23], v[68:71], 0
	v_mfma_f32_16x16x32_bf16 v[152:155], v[24:27], v[68:71], 0
	v_mfma_f32_16x16x32_bf16 v[156:159], v[28:31], v[68:71], 0
	v_mfma_f32_16x16x32_bf16 v[160:163], v[32:35], v[68:71], 0
	v_add_u32_e32 v196, v89, v93
	ds_write_b128 v196, v[132:135]
	ds_write_b128 v196, v[136:139] offset:64
	ds_write_b128 v196, v[140:143] offset:128
	ds_write_b128 v196, v[144:147] offset:192
	ds_write_b128 v196, v[148:151] offset:256
	ds_write_b128 v196, v[152:155] offset:320
	ds_write_b128 v196, v[156:159] offset:384
	ds_write_b128 v196, v[160:163] offset:448
	s_waitcnt lgkmcnt(0)
	s_and_b64 s[12:13], s[54:55], exec
	s_cbranch_scc0 .Ls5lt0_bwd
	ds_read_b64 v[164:165], v95
	ds_read_b64 v[166:167], v95 offset:528
	ds_read_b64 v[168:169], v95 offset:1056
	ds_read_b64 v[170:171], v95 offset:1584
	ds_read_b64 v[172:173], v95 offset:2112
	ds_read_b64 v[174:175], v95 offset:2640
	ds_read_b64 v[176:177], v95 offset:3168
	ds_read_b64 v[178:179], v95 offset:3696
	s_waitcnt lgkmcnt(7)
	v_fma_f32 v164, -v72, v121, v164
	v_fma_f32 v165, v72, v120, v165
	v_fma_f32 v164, v74, v120, v164
	v_fma_f32 v165, v74, v121, v165
	v_cvt_pk_bf16_f32 v197, v164, v165
	ds_write_b32 v97, v197 offset:8448
	ds_read_b64 v[180:181], v95 offset:4224
	s_waitcnt lgkmcnt(8)
	v_fma_f32 v166, -v72, v165, v166
	v_fma_f32 v167, v72, v164, v167
	v_fma_f32 v166, v74, v164, v166
	v_fma_f32 v167, v74, v165, v167
	v_cvt_pk_bf16_f32 v198, v166, v167
	ds_write_b32 v97, v198 offset:8720
	ds_read_b64 v[182:183], v95 offset:4752
	s_waitcnt lgkmcnt(9)
	v_fma_f32 v168, -v72, v167, v168
	v_fma_f32 v169, v72, v166, v169
	v_fma_f32 v168, v74, v166, v168
	v_fma_f32 v169, v74, v167, v169
	v_cvt_pk_bf16_f32 v197, v168, v169
	ds_write_b32 v97, v197 offset:8992
	ds_read_b64 v[184:185], v95 offset:5280
	s_waitcnt lgkmcnt(10)
	v_fma_f32 v170, -v72, v169, v170
	v_fma_f32 v171, v72, v168, v171
	v_fma_f32 v170, v74, v168, v170
	v_fma_f32 v171, v74, v169, v171
	v_cvt_pk_bf16_f32 v198, v170, v171
	ds_write_b32 v97, v198 offset:9264
	ds_read_b64 v[186:187], v95 offset:5808
	s_waitcnt lgkmcnt(11)
	v_fma_f32 v172, -v72, v171, v172
	v_fma_f32 v173, v72, v170, v173
	v_fma_f32 v172, v74, v170, v172
	v_fma_f32 v173, v74, v171, v173
	v_cvt_pk_bf16_f32 v197, v172, v173
	ds_write_b32 v97, v197 offset:9536
	ds_read_b64 v[188:189], v95 offset:6336
	s_waitcnt lgkmcnt(12)
	v_fma_f32 v174, -v72, v173, v174
	v_fma_f32 v175, v72, v172, v175
	v_fma_f32 v174, v74, v172, v174
	v_fma_f32 v175, v74, v173, v175
	v_cvt_pk_bf16_f32 v198, v174, v175
	ds_write_b32 v97, v198 offset:9808
	ds_read_b64 v[190:191], v95 offset:6864
	s_waitcnt lgkmcnt(13)
	v_fma_f32 v176, -v72, v175, v176
	v_fma_f32 v177, v72, v174, v177
	v_fma_f32 v176, v74, v174, v176
	v_fma_f32 v177, v74, v175, v177
	v_cvt_pk_bf16_f32 v197, v176, v177
	ds_write_b32 v97, v197 offset:10080
	ds_read_b64 v[192:193], v95 offset:7392
	s_waitcnt lgkmcnt(14)
	v_fma_f32 v178, -v72, v177, v178
	v_fma_f32 v179, v72, v176, v179
	v_fma_f32 v178, v74, v176, v178
	v_fma_f32 v179, v74, v177, v179
	v_cvt_pk_bf16_f32 v198, v178, v179
	ds_write_b32 v97, v198 offset:10352
	ds_read_b64 v[194:195], v95 offset:7920
	s_waitcnt lgkmcnt(14)
	v_fma_f32 v180, -v72, v179, v180
	v_fma_f32 v181, v72, v178, v181
	v_fma_f32 v180, v74, v178, v180
	v_fma_f32 v181, v74, v179, v181
	v_cvt_pk_bf16_f32 v197, v180, v181
	ds_write_b32 v97, v197 offset:10624
	s_waitcnt lgkmcnt(13)
	v_fma_f32 v182, -v72, v181, v182
	v_fma_f32 v183, v72, v180, v183
	v_fma_f32 v182, v74, v180, v182
	v_fma_f32 v183, v74, v181, v183
	v_cvt_pk_bf16_f32 v198, v182, v183
	ds_write_b32 v97, v198 offset:10896
	s_waitcnt lgkmcnt(12)
	v_fma_f32 v184, -v72, v183, v184
	v_fma_f32 v185, v72, v182, v185
	v_fma_f32 v184, v74, v182, v184
	v_fma_f32 v185, v74, v183, v185
	v_cvt_pk_bf16_f32 v197, v184, v185
	ds_write_b32 v97, v197 offset:11168
	s_waitcnt lgkmcnt(11)
	v_fma_f32 v186, -v72, v185, v186
	v_fma_f32 v187, v72, v184, v187
	v_fma_f32 v186, v74, v184, v186
	v_fma_f32 v187, v74, v185, v187
	v_cvt_pk_bf16_f32 v198, v186, v187
	ds_write_b32 v97, v198 offset:11440
	s_waitcnt lgkmcnt(10)
	v_fma_f32 v188, -v72, v187, v188
	v_fma_f32 v189, v72, v186, v189
	v_fma_f32 v188, v74, v186, v188
	v_fma_f32 v189, v74, v187, v189
	v_cvt_pk_bf16_f32 v197, v188, v189
	ds_write_b32 v97, v197 offset:11712
	s_waitcnt lgkmcnt(9)
	v_fma_f32 v190, -v72, v189, v190
	v_fma_f32 v191, v72, v188, v191
	v_fma_f32 v190, v74, v188, v190
	v_fma_f32 v191, v74, v189, v191
	v_cvt_pk_bf16_f32 v198, v190, v191
	ds_write_b32 v97, v198 offset:11984
	s_waitcnt lgkmcnt(8)
	v_fma_f32 v192, -v72, v191, v192
	v_fma_f32 v193, v72, v190, v193
	v_fma_f32 v192, v74, v190, v192
	v_fma_f32 v193, v74, v191, v193
	v_cvt_pk_bf16_f32 v197, v192, v193
	ds_write_b32 v97, v197 offset:12256
	s_waitcnt lgkmcnt(7)
	v_fma_f32 v194, -v72, v193, v194
	v_fma_f32 v195, v72, v192, v195
	v_fma_f32 v194, v74, v192, v194
	v_fma_f32 v195, v74, v193, v195
	v_cvt_pk_bf16_f32 v198, v194, v195
	ds_write_b32 v97, v198 offset:12528
	s_branch .Ls5lt0_join

.Ls5lt0_join:
	v_mov_b32_e32 v120, v194
	v_mov_b32_e32 v121, v195
	s_waitcnt lgkmcnt(0)
	v_add_u32_e32 v196, v99, v93
	ds_read_b128 v[132:135], v196 offset:8448
	ds_read_b128 v[136:139], v196 offset:8512
	ds_read_b128 v[140:143], v196 offset:8576
	ds_read_b128 v[144:147], v196 offset:8640
	s_not_b32 s12, s4
	s_add_i32 s15, s3, s12
	s_and_b64 s[12:13], s[54:55], exec
	s_cselect_b32 s12, s4, s15
	s_add_i32 s4, s4, 1
	s_waitcnt lgkmcnt(3)
	v_mfma_f32_16x16x32_bf16 v[202:205], v[48:51], v[132:135], 0
	s_waitcnt lgkmcnt(2)
	v_mfma_f32_16x16x32_bf16 v[202:205], v[52:55], v[136:139], v[202:205]
	s_waitcnt lgkmcnt(1)
	v_mfma_f32_16x16x32_bf16 v[202:205], v[56:59], v[140:143], v[202:205]
	s_waitcnt lgkmcnt(0)
	v_mfma_f32_16x16x32_bf16 v[202:205], v[60:63], v[144:147], v[202:205]
	v_lshl_add_u32 v200, s12, 4, v2
	v_ashrrev_i32_e32 v201, 31, v200
	v_lshlrev_b64 v[200:201], 12, v[200:201]
	v_lshl_add_u64 v[200:201], v[78:79], 0, v[200:201]
	s_nop 3
	v_cvt_pk_bf16_f32 v202, v202, v203
	v_cvt_pk_bf16_f32 v203, v204, v205
	global_store_dwordx2 v[200:201], v[202:203], off
	s_waitcnt vmcnt(6)
	v_mfma_f32_16x16x32_bf16 v[132:135], v[4:7], v[36:39], 0
	v_mfma_f32_16x16x32_bf16 v[136:139], v[8:11], v[36:39], 0
	v_mfma_f32_16x16x32_bf16 v[140:143], v[12:15], v[36:39], 0
	v_mfma_f32_16x16x32_bf16 v[144:147], v[16:19], v[36:39], 0
	v_mfma_f32_16x16x32_bf16 v[148:151], v[20:23], v[36:39], 0
	v_mfma_f32_16x16x32_bf16 v[152:155], v[24:27], v[36:39], 0
	v_mfma_f32_16x16x32_bf16 v[156:159], v[28:31], v[36:39], 0
	v_mfma_f32_16x16x32_bf16 v[160:163], v[32:35], v[36:39], 0
	v_add_u32_e32 v196, v89, v93
	ds_write_b128 v196, v[132:135]
	ds_write_b128 v196, v[136:139] offset:64
	ds_write_b128 v196, v[140:143] offset:128
	ds_write_b128 v196, v[144:147] offset:192
	ds_write_b128 v196, v[148:151] offset:256
	ds_write_b128 v196, v[152:155] offset:320
	ds_write_b128 v196, v[156:159] offset:384
	ds_write_b128 v196, v[160:163] offset:448
	s_waitcnt lgkmcnt(0)
	s_and_b64 s[12:13], s[54:55], exec
	s_cbranch_scc0 .Ls5lt1_bwd
	ds_read_b64 v[164:165], v95
	ds_read_b64 v[166:167], v95 offset:528
	ds_read_b64 v[168:169], v95 offset:1056
	ds_read_b64 v[170:171], v95 offset:1584
	ds_read_b64 v[172:173], v95 offset:2112
	ds_read_b64 v[174:175], v95 offset:2640
	ds_read_b64 v[176:177], v95 offset:3168
	ds_read_b64 v[178:179], v95 offset:3696
	s_waitcnt lgkmcnt(7)
	v_fma_f32 v164, -v72, v121, v164
	v_fma_f32 v165, v72, v120, v165
	v_fma_f32 v164, v74, v120, v164
	v_fma_f32 v165, v74, v121, v165
	v_cvt_pk_bf16_f32 v197, v164, v165
	ds_write_b32 v97, v197 offset:8448
	ds_read_b64 v[180:181], v95 offset:4224
	s_waitcnt lgkmcnt(8)
	v_fma_f32 v166, -v72, v165, v166
	v_fma_f32 v167, v72, v164, v167
	v_fma_f32 v166, v74, v164, v166
	v_fma_f32 v167, v74, v165, v167
	v_cvt_pk_bf16_f32 v198, v166, v167
	ds_write_b32 v97, v198 offset:8720
	ds_read_b64 v[182:183], v95 offset:4752
	s_waitcnt lgkmcnt(9)
	v_fma_f32 v168, -v72, v167, v168
	v_fma_f32 v169, v72, v166, v169
	v_fma_f32 v168, v74, v166, v168
	v_fma_f32 v169, v74, v167, v169
	v_cvt_pk_bf16_f32 v197, v168, v169
	ds_write_b32 v97, v197 offset:8992
	ds_read_b64 v[184:185], v95 offset:5280
	s_waitcnt lgkmcnt(10)
	v_fma_f32 v170, -v72, v169, v170
	v_fma_f32 v171, v72, v168, v171
	v_fma_f32 v170, v74, v168, v170
	v_fma_f32 v171, v74, v169, v171
	v_cvt_pk_bf16_f32 v198, v170, v171
	ds_write_b32 v97, v198 offset:9264
	ds_read_b64 v[186:187], v95 offset:5808
	s_waitcnt lgkmcnt(11)
	v_fma_f32 v172, -v72, v171, v172
	v_fma_f32 v173, v72, v170, v173
	v_fma_f32 v172, v74, v170, v172
	v_fma_f32 v173, v74, v171, v173
	v_cvt_pk_bf16_f32 v197, v172, v173
	ds_write_b32 v97, v197 offset:9536
	ds_read_b64 v[188:189], v95 offset:6336
	s_waitcnt lgkmcnt(12)
	v_fma_f32 v174, -v72, v173, v174
	v_fma_f32 v175, v72, v172, v175
	v_fma_f32 v174, v74, v172, v174
	v_fma_f32 v175, v74, v173, v175
	v_cvt_pk_bf16_f32 v198, v174, v175
	ds_write_b32 v97, v198 offset:9808
	ds_read_b64 v[190:191], v95 offset:6864
	s_waitcnt lgkmcnt(13)
	v_fma_f32 v176, -v72, v175, v176
	v_fma_f32 v177, v72, v174, v177
	v_fma_f32 v176, v74, v174, v176
	v_fma_f32 v177, v74, v175, v177
	v_cvt_pk_bf16_f32 v197, v176, v177
	ds_write_b32 v97, v197 offset:10080
	ds_read_b64 v[192:193], v95 offset:7392
	s_waitcnt lgkmcnt(14)
	v_fma_f32 v178, -v72, v177, v178
	v_fma_f32 v179, v72, v176, v179
	v_fma_f32 v178, v74, v176, v178
	v_fma_f32 v179, v74, v177, v179
	v_cvt_pk_bf16_f32 v198, v178, v179
	ds_write_b32 v97, v198 offset:10352
	ds_read_b64 v[194:195], v95 offset:7920
	s_waitcnt lgkmcnt(14)
	v_fma_f32 v180, -v72, v179, v180
	v_fma_f32 v181, v72, v178, v181
	v_fma_f32 v180, v74, v178, v180
	v_fma_f32 v181, v74, v179, v181
	v_cvt_pk_bf16_f32 v197, v180, v181
	ds_write_b32 v97, v197 offset:10624
	s_waitcnt lgkmcnt(13)
	v_fma_f32 v182, -v72, v181, v182
	v_fma_f32 v183, v72, v180, v183
	v_fma_f32 v182, v74, v180, v182
	v_fma_f32 v183, v74, v181, v183
	v_cvt_pk_bf16_f32 v198, v182, v183
	ds_write_b32 v97, v198 offset:10896
	s_waitcnt lgkmcnt(12)
	v_fma_f32 v184, -v72, v183, v184
	v_fma_f32 v185, v72, v182, v185
	v_fma_f32 v184, v74, v182, v184
	v_fma_f32 v185, v74, v183, v185
	v_cvt_pk_bf16_f32 v197, v184, v185
	ds_write_b32 v97, v197 offset:11168
	s_waitcnt lgkmcnt(11)
	v_fma_f32 v186, -v72, v185, v186
	v_fma_f32 v187, v72, v184, v187
	v_fma_f32 v186, v74, v184, v186
	v_fma_f32 v187, v74, v185, v187
	v_cvt_pk_bf16_f32 v198, v186, v187
	ds_write_b32 v97, v198 offset:11440
	s_waitcnt lgkmcnt(10)
	v_fma_f32 v188, -v72, v187, v188
	v_fma_f32 v189, v72, v186, v189
	v_fma_f32 v188, v74, v186, v188
	v_fma_f32 v189, v74, v187, v189
	v_cvt_pk_bf16_f32 v197, v188, v189
	ds_write_b32 v97, v197 offset:11712
	s_waitcnt lgkmcnt(9)
	v_fma_f32 v190, -v72, v189, v190
	v_fma_f32 v191, v72, v188, v191
	v_fma_f32 v190, v74, v188, v190
	v_fma_f32 v191, v74, v189, v191
	v_cvt_pk_bf16_f32 v198, v190, v191
	ds_write_b32 v97, v198 offset:11984
	s_waitcnt lgkmcnt(8)
	v_fma_f32 v192, -v72, v191, v192
	v_fma_f32 v193, v72, v190, v193
	v_fma_f32 v192, v74, v190, v192
	v_fma_f32 v193, v74, v191, v193
	v_cvt_pk_bf16_f32 v197, v192, v193
	ds_write_b32 v97, v197 offset:12256
	s_waitcnt lgkmcnt(7)
	v_fma_f32 v194, -v72, v193, v194
	v_fma_f32 v195, v72, v192, v195
	v_fma_f32 v194, v74, v192, v194
	v_fma_f32 v195, v74, v193, v195
	v_cvt_pk_bf16_f32 v198, v194, v195
	ds_write_b32 v97, v198 offset:12528
	s_branch .Ls5lt1_join

.Ls5lt1_join:
	v_mov_b32_e32 v120, v194
	v_mov_b32_e32 v121, v195
	s_waitcnt lgkmcnt(0)
	v_add_u32_e32 v196, v99, v93
	ds_read_b128 v[132:135], v196 offset:8448
	ds_read_b128 v[136:139], v196 offset:8512
	ds_read_b128 v[140:143], v196 offset:8576
	ds_read_b128 v[144:147], v196 offset:8640
	s_not_b32 s12, s4
	s_add_i32 s15, s3, s12
	s_and_b64 s[12:13], s[54:55], exec
	s_cselect_b32 s12, s4, s15
	s_add_i32 s4, s4, 1
	s_waitcnt lgkmcnt(3)
	v_mfma_f32_16x16x32_bf16 v[202:205], v[48:51], v[132:135], 0
	s_waitcnt lgkmcnt(2)
	v_mfma_f32_16x16x32_bf16 v[202:205], v[52:55], v[136:139], v[202:205]
	s_waitcnt lgkmcnt(1)
	v_mfma_f32_16x16x32_bf16 v[202:205], v[56:59], v[140:143], v[202:205]
	s_waitcnt lgkmcnt(0)
	v_mfma_f32_16x16x32_bf16 v[202:205], v[60:63], v[144:147], v[202:205]
	v_lshl_add_u32 v200, s12, 4, v2
	v_ashrrev_i32_e32 v201, 31, v200
	v_lshlrev_b64 v[200:201], 12, v[200:201]
	v_lshl_add_u64 v[200:201], v[78:79], 0, v[200:201]
	s_nop 3
	v_cvt_pk_bf16_f32 v202, v202, v203
	v_cvt_pk_bf16_f32 v203, v204, v205
	global_store_dwordx2 v[200:201], v[202:203], off
	s_waitcnt vmcnt(5)
	v_mfma_f32_16x16x32_bf16 v[132:135], v[4:7], v[40:43], 0
	v_mfma_f32_16x16x32_bf16 v[136:139], v[8:11], v[40:43], 0
	v_mfma_f32_16x16x32_bf16 v[140:143], v[12:15], v[40:43], 0
	v_mfma_f32_16x16x32_bf16 v[144:147], v[16:19], v[40:43], 0
	v_mfma_f32_16x16x32_bf16 v[148:151], v[20:23], v[40:43], 0
	v_mfma_f32_16x16x32_bf16 v[152:155], v[24:27], v[40:43], 0
	v_mfma_f32_16x16x32_bf16 v[156:159], v[28:31], v[40:43], 0
	v_mfma_f32_16x16x32_bf16 v[160:163], v[32:35], v[40:43], 0
	v_add_u32_e32 v196, v89, v93
	ds_write_b128 v196, v[132:135]
	ds_write_b128 v196, v[136:139] offset:64
	ds_write_b128 v196, v[140:143] offset:128
	ds_write_b128 v196, v[144:147] offset:192
	ds_write_b128 v196, v[148:151] offset:256
	ds_write_b128 v196, v[152:155] offset:320
	ds_write_b128 v196, v[156:159] offset:384
	ds_write_b128 v196, v[160:163] offset:448
	s_waitcnt lgkmcnt(0)
	s_and_b64 s[12:13], s[54:55], exec
	s_cbranch_scc0 .Ls5lt2_bwd
	ds_read_b64 v[164:165], v95
	ds_read_b64 v[166:167], v95 offset:528
	ds_read_b64 v[168:169], v95 offset:1056
	ds_read_b64 v[170:171], v95 offset:1584
	ds_read_b64 v[172:173], v95 offset:2112
	ds_read_b64 v[174:175], v95 offset:2640
	ds_read_b64 v[176:177], v95 offset:3168
	ds_read_b64 v[178:179], v95 offset:3696
	s_waitcnt lgkmcnt(7)
	v_fma_f32 v164, -v72, v121, v164
	v_fma_f32 v165, v72, v120, v165
	v_fma_f32 v164, v74, v120, v164
	v_fma_f32 v165, v74, v121, v165
	v_cvt_pk_bf16_f32 v197, v164, v165
	ds_write_b32 v97, v197 offset:8448
	ds_read_b64 v[180:181], v95 offset:4224
	s_waitcnt lgkmcnt(8)
	v_fma_f32 v166, -v72, v165, v166
	v_fma_f32 v167, v72, v164, v167
	v_fma_f32 v166, v74, v164, v166
	v_fma_f32 v167, v74, v165, v167
	v_cvt_pk_bf16_f32 v198, v166, v167
	ds_write_b32 v97, v198 offset:8720
	ds_read_b64 v[182:183], v95 offset:4752
	s_waitcnt lgkmcnt(9)
	v_fma_f32 v168, -v72, v167, v168
	v_fma_f32 v169, v72, v166, v169
	v_fma_f32 v168, v74, v166, v168
	v_fma_f32 v169, v74, v167, v169
	v_cvt_pk_bf16_f32 v197, v168, v169
	ds_write_b32 v97, v197 offset:8992
	ds_read_b64 v[184:185], v95 offset:5280
	s_waitcnt lgkmcnt(10)
	v_fma_f32 v170, -v72, v169, v170
	v_fma_f32 v171, v72, v168, v171
	v_fma_f32 v170, v74, v168, v170
	v_fma_f32 v171, v74, v169, v171
	v_cvt_pk_bf16_f32 v198, v170, v171
	ds_write_b32 v97, v198 offset:9264
	ds_read_b64 v[186:187], v95 offset:5808
	s_waitcnt lgkmcnt(11)
	v_fma_f32 v172, -v72, v171, v172
	v_fma_f32 v173, v72, v170, v173
	v_fma_f32 v172, v74, v170, v172
	v_fma_f32 v173, v74, v171, v173
	v_cvt_pk_bf16_f32 v197, v172, v173
	ds_write_b32 v97, v197 offset:9536
	ds_read_b64 v[188:189], v95 offset:6336
	s_waitcnt lgkmcnt(12)
	v_fma_f32 v174, -v72, v173, v174
	v_fma_f32 v175, v72, v172, v175
	v_fma_f32 v174, v74, v172, v174
	v_fma_f32 v175, v74, v173, v175
	v_cvt_pk_bf16_f32 v198, v174, v175
	ds_write_b32 v97, v198 offset:9808
	ds_read_b64 v[190:191], v95 offset:6864
	s_waitcnt lgkmcnt(13)
	v_fma_f32 v176, -v72, v175, v176
	v_fma_f32 v177, v72, v174, v177
	v_fma_f32 v176, v74, v174, v176
	v_fma_f32 v177, v74, v175, v177
	v_cvt_pk_bf16_f32 v197, v176, v177
	ds_write_b32 v97, v197 offset:10080
	ds_read_b64 v[192:193], v95 offset:7392
	s_waitcnt lgkmcnt(14)
	v_fma_f32 v178, -v72, v177, v178
	v_fma_f32 v179, v72, v176, v179
	v_fma_f32 v178, v74, v176, v178
	v_fma_f32 v179, v74, v177, v179
	v_cvt_pk_bf16_f32 v198, v178, v179
	ds_write_b32 v97, v198 offset:10352
	ds_read_b64 v[194:195], v95 offset:7920
	s_waitcnt lgkmcnt(14)
	v_fma_f32 v180, -v72, v179, v180
	v_fma_f32 v181, v72, v178, v181
	v_fma_f32 v180, v74, v178, v180
	v_fma_f32 v181, v74, v179, v181
	v_cvt_pk_bf16_f32 v197, v180, v181
	ds_write_b32 v97, v197 offset:10624
	s_waitcnt lgkmcnt(13)
	v_fma_f32 v182, -v72, v181, v182
	v_fma_f32 v183, v72, v180, v183
	v_fma_f32 v182, v74, v180, v182
	v_fma_f32 v183, v74, v181, v183
	v_cvt_pk_bf16_f32 v198, v182, v183
	ds_write_b32 v97, v198 offset:10896
	s_waitcnt lgkmcnt(12)
	v_fma_f32 v184, -v72, v183, v184
	v_fma_f32 v185, v72, v182, v185
	v_fma_f32 v184, v74, v182, v184
	v_fma_f32 v185, v74, v183, v185
	v_cvt_pk_bf16_f32 v197, v184, v185
	ds_write_b32 v97, v197 offset:11168
	s_waitcnt lgkmcnt(11)
	v_fma_f32 v186, -v72, v185, v186
	v_fma_f32 v187, v72, v184, v187
	v_fma_f32 v186, v74, v184, v186
	v_fma_f32 v187, v74, v185, v187
	v_cvt_pk_bf16_f32 v198, v186, v187
	ds_write_b32 v97, v198 offset:11440
	s_waitcnt lgkmcnt(10)
	v_fma_f32 v188, -v72, v187, v188
	v_fma_f32 v189, v72, v186, v189
	v_fma_f32 v188, v74, v186, v188
	v_fma_f32 v189, v74, v187, v189
	v_cvt_pk_bf16_f32 v197, v188, v189
	ds_write_b32 v97, v197 offset:11712
	s_waitcnt lgkmcnt(9)
	v_fma_f32 v190, -v72, v189, v190
	v_fma_f32 v191, v72, v188, v191
	v_fma_f32 v190, v74, v188, v190
	v_fma_f32 v191, v74, v189, v191
	v_cvt_pk_bf16_f32 v198, v190, v191
	ds_write_b32 v97, v198 offset:11984
	s_waitcnt lgkmcnt(8)
	v_fma_f32 v192, -v72, v191, v192
	v_fma_f32 v193, v72, v190, v193
	v_fma_f32 v192, v74, v190, v192
	v_fma_f32 v193, v74, v191, v193
	v_cvt_pk_bf16_f32 v197, v192, v193
	ds_write_b32 v97, v197 offset:12256
	s_waitcnt lgkmcnt(7)
	v_fma_f32 v194, -v72, v193, v194
	v_fma_f32 v195, v72, v192, v195
	v_fma_f32 v194, v74, v192, v194
	v_fma_f32 v195, v74, v193, v195
	v_cvt_pk_bf16_f32 v198, v194, v195
	ds_write_b32 v97, v198 offset:12528
	s_branch .Ls5lt2_join

.Ls5lt2_join:
	v_mov_b32_e32 v120, v194
	v_mov_b32_e32 v121, v195
	s_waitcnt lgkmcnt(0)
	v_add_u32_e32 v196, v99, v93
	ds_read_b128 v[132:135], v196 offset:8448
	ds_read_b128 v[136:139], v196 offset:8512
	ds_read_b128 v[140:143], v196 offset:8576
	ds_read_b128 v[144:147], v196 offset:8640
	s_not_b32 s12, s4
	s_add_i32 s15, s3, s12
	s_and_b64 s[12:13], s[54:55], exec
	s_cselect_b32 s12, s4, s15
	s_add_i32 s4, s4, 1
	s_waitcnt lgkmcnt(3)
	v_mfma_f32_16x16x32_bf16 v[202:205], v[48:51], v[132:135], 0
	s_waitcnt lgkmcnt(2)
	v_mfma_f32_16x16x32_bf16 v[202:205], v[52:55], v[136:139], v[202:205]
	s_waitcnt lgkmcnt(1)
	v_mfma_f32_16x16x32_bf16 v[202:205], v[56:59], v[140:143], v[202:205]
	s_waitcnt lgkmcnt(0)
	v_mfma_f32_16x16x32_bf16 v[202:205], v[60:63], v[144:147], v[202:205]
	v_lshl_add_u32 v200, s12, 4, v2
	v_ashrrev_i32_e32 v201, 31, v200
	v_lshlrev_b64 v[200:201], 12, v[200:201]
	v_lshl_add_u64 v[200:201], v[78:79], 0, v[200:201]
	s_nop 3
	v_cvt_pk_bf16_f32 v202, v202, v203
	v_cvt_pk_bf16_f32 v203, v204, v205
	global_store_dwordx2 v[200:201], v[202:203], off
	s_waitcnt vmcnt(4)
	v_mfma_f32_16x16x32_bf16 v[132:135], v[4:7], v[44:47], 0
	v_mfma_f32_16x16x32_bf16 v[136:139], v[8:11], v[44:47], 0
	v_mfma_f32_16x16x32_bf16 v[140:143], v[12:15], v[44:47], 0
	v_mfma_f32_16x16x32_bf16 v[144:147], v[16:19], v[44:47], 0
	v_mfma_f32_16x16x32_bf16 v[148:151], v[20:23], v[44:47], 0
	v_mfma_f32_16x16x32_bf16 v[152:155], v[24:27], v[44:47], 0
	v_mfma_f32_16x16x32_bf16 v[156:159], v[28:31], v[44:47], 0
	v_mfma_f32_16x16x32_bf16 v[160:163], v[32:35], v[44:47], 0
	v_add_u32_e32 v196, v89, v93
	ds_write_b128 v196, v[132:135]
	ds_write_b128 v196, v[136:139] offset:64
	ds_write_b128 v196, v[140:143] offset:128
	ds_write_b128 v196, v[144:147] offset:192
	ds_write_b128 v196, v[148:151] offset:256
	ds_write_b128 v196, v[152:155] offset:320
	ds_write_b128 v196, v[156:159] offset:384
	ds_write_b128 v196, v[160:163] offset:448
	s_waitcnt lgkmcnt(0)
	s_and_b64 s[12:13], s[54:55], exec
	s_cbranch_scc0 .Ls5lt3_bwd
	ds_read_b64 v[164:165], v95
	ds_read_b64 v[166:167], v95 offset:528
	ds_read_b64 v[168:169], v95 offset:1056
	ds_read_b64 v[170:171], v95 offset:1584
	ds_read_b64 v[172:173], v95 offset:2112
	ds_read_b64 v[174:175], v95 offset:2640
	ds_read_b64 v[176:177], v95 offset:3168
	ds_read_b64 v[178:179], v95 offset:3696
	s_waitcnt lgkmcnt(7)
	v_fma_f32 v164, -v72, v121, v164
	v_fma_f32 v165, v72, v120, v165
	v_fma_f32 v164, v74, v120, v164
	v_fma_f32 v165, v74, v121, v165
	v_cvt_pk_bf16_f32 v197, v164, v165
	ds_write_b32 v97, v197 offset:8448
	ds_read_b64 v[180:181], v95 offset:4224
	s_waitcnt lgkmcnt(8)
	v_fma_f32 v166, -v72, v165, v166
	v_fma_f32 v167, v72, v164, v167
	v_fma_f32 v166, v74, v164, v166
	v_fma_f32 v167, v74, v165, v167
	v_cvt_pk_bf16_f32 v198, v166, v167
	ds_write_b32 v97, v198 offset:8720
	ds_read_b64 v[182:183], v95 offset:4752
	s_waitcnt lgkmcnt(9)
	v_fma_f32 v168, -v72, v167, v168
	v_fma_f32 v169, v72, v166, v169
	v_fma_f32 v168, v74, v166, v168
	v_fma_f32 v169, v74, v167, v169
	v_cvt_pk_bf16_f32 v197, v168, v169
	ds_write_b32 v97, v197 offset:8992
	ds_read_b64 v[184:185], v95 offset:5280
	s_waitcnt lgkmcnt(10)
	v_fma_f32 v170, -v72, v169, v170
	v_fma_f32 v171, v72, v168, v171
	v_fma_f32 v170, v74, v168, v170
	v_fma_f32 v171, v74, v169, v171
	v_cvt_pk_bf16_f32 v198, v170, v171
	ds_write_b32 v97, v198 offset:9264
	ds_read_b64 v[186:187], v95 offset:5808
	s_waitcnt lgkmcnt(11)
	v_fma_f32 v172, -v72, v171, v172
	v_fma_f32 v173, v72, v170, v173
	v_fma_f32 v172, v74, v170, v172
	v_fma_f32 v173, v74, v171, v173
	v_cvt_pk_bf16_f32 v197, v172, v173
	ds_write_b32 v97, v197 offset:9536
	ds_read_b64 v[188:189], v95 offset:6336
	s_waitcnt lgkmcnt(12)
	v_fma_f32 v174, -v72, v173, v174
	v_fma_f32 v175, v72, v172, v175
	v_fma_f32 v174, v74, v172, v174
	v_fma_f32 v175, v74, v173, v175
	v_cvt_pk_bf16_f32 v198, v174, v175
	ds_write_b32 v97, v198 offset:9808
	ds_read_b64 v[190:191], v95 offset:6864
	s_waitcnt lgkmcnt(13)
	v_fma_f32 v176, -v72, v175, v176
	v_fma_f32 v177, v72, v174, v177
	v_fma_f32 v176, v74, v174, v176
	v_fma_f32 v177, v74, v175, v177
	v_cvt_pk_bf16_f32 v197, v176, v177
	ds_write_b32 v97, v197 offset:10080
	ds_read_b64 v[192:193], v95 offset:7392
	s_waitcnt lgkmcnt(14)
	v_fma_f32 v178, -v72, v177, v178
	v_fma_f32 v179, v72, v176, v179
	v_fma_f32 v178, v74, v176, v178
	v_fma_f32 v179, v74, v177, v179
	v_cvt_pk_bf16_f32 v198, v178, v179
	ds_write_b32 v97, v198 offset:10352
	ds_read_b64 v[194:195], v95 offset:7920
	s_waitcnt lgkmcnt(14)
	v_fma_f32 v180, -v72, v179, v180
	v_fma_f32 v181, v72, v178, v181
	v_fma_f32 v180, v74, v178, v180
	v_fma_f32 v181, v74, v179, v181
	v_cvt_pk_bf16_f32 v197, v180, v181
	ds_write_b32 v97, v197 offset:10624
	s_waitcnt lgkmcnt(13)
	v_fma_f32 v182, -v72, v181, v182
	v_fma_f32 v183, v72, v180, v183
	v_fma_f32 v182, v74, v180, v182
	v_fma_f32 v183, v74, v181, v183
	v_cvt_pk_bf16_f32 v198, v182, v183
	ds_write_b32 v97, v198 offset:10896
	s_waitcnt lgkmcnt(12)
	v_fma_f32 v184, -v72, v183, v184
	v_fma_f32 v185, v72, v182, v185
	v_fma_f32 v184, v74, v182, v184
	v_fma_f32 v185, v74, v183, v185
	v_cvt_pk_bf16_f32 v197, v184, v185
	ds_write_b32 v97, v197 offset:11168
	s_waitcnt lgkmcnt(11)
	v_fma_f32 v186, -v72, v185, v186
	v_fma_f32 v187, v72, v184, v187
	v_fma_f32 v186, v74, v184, v186
	v_fma_f32 v187, v74, v185, v187
	v_cvt_pk_bf16_f32 v198, v186, v187
	ds_write_b32 v97, v198 offset:11440
	s_waitcnt lgkmcnt(10)
	v_fma_f32 v188, -v72, v187, v188
	v_fma_f32 v189, v72, v186, v189
	v_fma_f32 v188, v74, v186, v188
	v_fma_f32 v189, v74, v187, v189
	v_cvt_pk_bf16_f32 v197, v188, v189
	ds_write_b32 v97, v197 offset:11712
	s_waitcnt lgkmcnt(9)
	v_fma_f32 v190, -v72, v189, v190
	v_fma_f32 v191, v72, v188, v191
	v_fma_f32 v190, v74, v188, v190
	v_fma_f32 v191, v74, v189, v191
	v_cvt_pk_bf16_f32 v198, v190, v191
	ds_write_b32 v97, v198 offset:11984
	s_waitcnt lgkmcnt(8)
	v_fma_f32 v192, -v72, v191, v192
	v_fma_f32 v193, v72, v190, v193
	v_fma_f32 v192, v74, v190, v192
	v_fma_f32 v193, v74, v191, v193
	v_cvt_pk_bf16_f32 v197, v192, v193
	ds_write_b32 v97, v197 offset:12256
	s_waitcnt lgkmcnt(7)
	v_fma_f32 v194, -v72, v193, v194
	v_fma_f32 v195, v72, v192, v195
	v_fma_f32 v194, v74, v192, v194
	v_fma_f32 v195, v74, v193, v195
	v_cvt_pk_bf16_f32 v198, v194, v195
	ds_write_b32 v97, v198 offset:12528
	s_branch .Ls5lt3_join

.Ls5lt3_join:
	v_mov_b32_e32 v120, v194
	v_mov_b32_e32 v121, v195
	s_waitcnt lgkmcnt(0)
	v_add_u32_e32 v196, v99, v93
	ds_read_b128 v[132:135], v196 offset:8448
	ds_read_b128 v[136:139], v196 offset:8512
	ds_read_b128 v[140:143], v196 offset:8576
	ds_read_b128 v[144:147], v196 offset:8640
	s_not_b32 s12, s4
	s_add_i32 s15, s3, s12
	s_and_b64 s[12:13], s[54:55], exec
	s_cselect_b32 s12, s4, s15
	s_add_i32 s4, s4, 1
	s_waitcnt lgkmcnt(3)
	v_mfma_f32_16x16x32_bf16 v[202:205], v[48:51], v[132:135], 0
	s_waitcnt lgkmcnt(2)
	v_mfma_f32_16x16x32_bf16 v[202:205], v[52:55], v[136:139], v[202:205]
	s_waitcnt lgkmcnt(1)
	v_mfma_f32_16x16x32_bf16 v[202:205], v[56:59], v[140:143], v[202:205]
	s_waitcnt lgkmcnt(0)
	v_mfma_f32_16x16x32_bf16 v[202:205], v[60:63], v[144:147], v[202:205]
	v_lshl_add_u32 v200, s12, 4, v2
	v_ashrrev_i32_e32 v201, 31, v200
	v_lshlrev_b64 v[200:201], 12, v[200:201]
	v_lshl_add_u64 v[200:201], v[78:79], 0, v[200:201]
	s_nop 3
	v_cvt_pk_bf16_f32 v202, v202, v203
	v_cvt_pk_bf16_f32 v203, v204, v205
	global_store_dwordx2 v[200:201], v[202:203], off
	s_branch .LBB0_916
